# LDS-DMA ring K-loop in all five ctx pre-pass GEMMs
# speedup vs baseline: 1.1177x; 1.0049x over previous
; template <bool BNN, class AL, class BL>
; __device__ __forceinline__ void gemm_tile(const AL& al, const BL& bl, int K, u16* smem, f32x16 (&acc)[2][2]) {
;     ...
;   G_LOAD(ra0, rb0, 0)
;   G_STORE(ra0, rb0, 0)
;   if (nkt > 1) G_LOAD(ra1, rb1, 1)
;   __syncthreads();
;   for (int kt = 0; kt < nkt; kt += 2) {
;     if (kt + 2 < nkt) G_LOAD(ra0, rb0, kt + 2)
;     G_COMPUTE(0)
;     if (kt + 1 < nkt) G_STORE(ra1, rb1, 1)
;     __syncthreads();
;     if (kt + 1 >= nkt) break;
;     if (kt + 3 < nkt) G_LOAD(ra1, rb1, kt + 3)
;     G_COMPUTE(1)
;     if (kt + 2 < nkt) G_STORE(ra0, rb0, 0)
;     __syncthreads();
;   }
; __device__ __forceinline__ void gemm_nt_phase(const u16* A, int lda, const u16* Bt, int ldb, u16* C, int ldc,
;                               int Mt, int Nt, int K, int qcols, float qscale, u16* smem,
;                               u16* vtx = nullptr, u16* vtc = nullptr, u16* smv = nullptr) {
;   if (smv != nullptr) {
;     const int NtS = Nt * 2, nS = 8 * NtS;
;     for (int t = VBID; t < nS; t += VGRID) {
;       const int ms = t / NtS, ns = t - ms * NtS;
;       const u16* Ab = A + (long)(N_X + ms * 128) * lda;
;       const u16* Bb = Bt + (long)ns * 128 * ldb;
;       auto al = [=](int r, int k) { return ldg16(Ab + (unsigned)(r * lda + k)); };
;       auto bl = [=](int r, int k) { return ldg16(Bb + (unsigned)(r * ldb + k)); };
;       f32x16 acc[2][2];
;       gemm_tile<false>(al, bl, K, smv, acc);
.LBB0_170:
	s_waitcnt vmcnt(0)
	s_barrier
	v_readfirstlane_b32 s98, v153
	v_bfe_u32 v108, v152, 6, 2
	v_readlane_b32 s100, v252, 0
	v_readlane_b32 s101, v252, 1
	v_readfirstlane_b32 s99, v108
	s_nop 3
	s_sub_u32 s100, s100, 0x170
	s_subb_u32 s101, s101, 0
	s_lshl_b32 vcc_lo, s2, 1
	s_add_u32 vcc_lo, vcc_lo, s98
	s_mul_i32 vcc_hi, vcc_lo, 5462
	s_lshr_b32 vcc_hi, vcc_hi, 16
	s_mul_i32 m0, vcc_hi, 12
	s_sub_u32 vcc_lo, vcc_lo, m0
	v_mul_u32_u24_e32 v108, 0x12000, v153
	v_add_u32_e32 v108, 16, v108
	v_and_b32_e32 v109, 31, v152
	v_bfe_u32 v110, v152, 2, 2
	v_bfe_u32 v111, v152, 5, 1
	v_xor_b32_e32 v112, v111, v110
	v_lshlrev_b32_e32 v112, 4, v112
	v_xor_b32_e32 v113, 32, v112
	v_bfe_u32 v114, v152, 7, 1
	v_lshl_add_u32 v114, v114, 6, v109
	v_lshl_add_u32 v114, v114, 6, v108
	v_bfe_u32 v115, v152, 6, 1
	v_lshl_add_u32 v115, v115, 6, v109
	v_lshl_add_u32 v115, v115, 6, v108
	v_add_u32_e32 v104, v114, v112
	v_add_u32_e32 v105, v114, v113
	v_add_u32_e32 v115, 0x2000, v115
	v_add_u32_e32 v106, v115, v112
	v_add_u32_e32 v107, v115, v113
	v_bfe_u32 v109, v152, 2, 4
	v_bfe_u32 v110, v152, 4, 2
	v_and_b32_e32 v111, 3, v152
	v_xor_b32_e32 v110, v111, v110
	v_bfe_u32 v111, v152, 6, 2
	v_lshl_add_u32 v109, v111, 5, v109
	s_mov_b32 m0, 0x800
	v_mul_lo_u32 v112, v109, m0
	v_lshl_add_u32 v112, v110, 4, v112
	s_lshl_b32 s98, s98, 0
	s_mov_b32 s99, s99
	s_lshl_b32 vcc_hi, vcc_hi, 8
	s_or_b32 s98, s98, vcc_hi
	s_lshl_b32 vcc_lo, vcc_lo, 16
	s_or_b32 s98, s98, vcc_lo
	s_load_dwordx2 s[100:101], s[100:101], 0x140
	s_bfe_u32 m0, s98, 0x80008
	s_lshl_b32 m0, m0, 7
	s_add_u32 m0, m0, 0x8000
	s_mul_i32 m0, m0, 0x800
	s_waitcnt lgkmcnt(0)
	s_add_u32 s100, s100, m0
	s_addc_u32 s101, s101, 0
	v_mov_b32_e32 v113, s101
	v_add_co_u32_e32 v96, vcc, s100, v112
	s_nop 1
	v_addc_co_u32_e32 v97, vcc, 0, v113, vcc
	v_add_co_u32_e32 v98, vcc, 0x8000, v96
	s_nop 1
	v_addc_co_u32_e32 v99, vcc, 0, v97, vcc
	v_readlane_b32 s100, v252, 0
	v_readlane_b32 s101, v252, 1
	s_nop 3
	s_sub_u32 s100, s100, 0x170
	s_subb_u32 s101, s101, 0
	s_load_dwordx2 s[100:101], s[100:101], 0xd0
	s_bfe_u32 m0, s98, 0x80010
	s_lshl_b32 m0, m0, 7
	s_mul_i32 m0, m0, 0x800
	s_waitcnt lgkmcnt(0)
	s_add_u32 s100, s100, m0
	s_addc_u32 s101, s101, 0
	v_mov_b32_e32 v113, s101
	v_add_co_u32_e32 v100, vcc, s100, v112
	s_nop 1
	v_addc_co_u32_e32 v101, vcc, 0, v113, vcc
	v_add_co_u32_e32 v102, vcc, 0x8000, v100
	s_nop 1
	v_addc_co_u32_e32 v103, vcc, 0, v101, vcc
	s_and_b32 m0, s98, 1
	s_mul_i32 m0, m0, 0x12000
	s_lshl_b32 s99, s99, 11
	s_add_u32 s98, m0, s99
	s_add_u32 s98, s98, 16
	s_add_u32 m0, s98, 0x0
	s_nop 0
	global_load_lds_dwordx4 v[96:97], off
	s_add_u32 m0, s98, 0x400
	s_nop 0
	global_load_lds_dwordx4 v[98:99], off
	s_add_u32 m0, s98, 0x2000
	s_nop 0
	global_load_lds_dwordx4 v[100:101], off
	s_add_u32 m0, s98, 0x2400
	s_nop 0
	global_load_lds_dwordx4 v[102:103], off
	v_lshl_add_u64 v[96:97], v[96:97], 0, 64
	v_lshl_add_u64 v[98:99], v[98:99], 0, 64
	v_lshl_add_u64 v[100:101], v[100:101], 0, 64
	v_lshl_add_u64 v[102:103], v[102:103], 0, 64
	s_add_u32 m0, s98, 0x4000
	s_nop 0
	global_load_lds_dwordx4 v[96:97], off
	s_add_u32 m0, s98, 0x4400
	s_nop 0
	global_load_lds_dwordx4 v[98:99], off
	s_add_u32 m0, s98, 0x6000
	s_nop 0
	global_load_lds_dwordx4 v[100:101], off
	s_add_u32 m0, s98, 0x6400
	s_nop 0
	global_load_lds_dwordx4 v[102:103], off
	v_lshl_add_u64 v[96:97], v[96:97], 0, 64
	v_lshl_add_u64 v[98:99], v[98:99], 0, 64
	v_lshl_add_u64 v[100:101], v[100:101], 0, 64
	v_lshl_add_u64 v[102:103], v[102:103], 0, 64
	s_add_u32 m0, s98, 0x8000
	s_nop 0
	global_load_lds_dwordx4 v[96:97], off
	s_add_u32 m0, s98, 0x8400
	s_nop 0
	global_load_lds_dwordx4 v[98:99], off
	s_add_u32 m0, s98, 0xa000
	s_nop 0
	global_load_lds_dwordx4 v[100:101], off
	s_add_u32 m0, s98, 0xa400
	s_nop 0
	global_load_lds_dwordx4 v[102:103], off
	v_lshl_add_u64 v[96:97], v[96:97], 0, 64
	v_lshl_add_u64 v[98:99], v[98:99], 0, 64
	v_lshl_add_u64 v[100:101], v[100:101], 0, 64
	v_lshl_add_u64 v[102:103], v[102:103], 0, 64
	s_waitcnt vmcnt(8)
	s_barrier
	ds_read_b128 v[64:67], v104 offset:0
	ds_read_b128 v[68:71], v104 offset:2048
	ds_read_b128 v[72:75], v106 offset:0
	ds_read_b128 v[76:79], v106 offset:2048
	s_add_u32 m0, s98, 0xc000
	s_nop 0
	global_load_lds_dwordx4 v[96:97], off
	s_add_u32 m0, s98, 0xc400
	s_nop 0
	global_load_lds_dwordx4 v[98:99], off
	s_add_u32 m0, s98, 0xe000
	s_nop 0
	global_load_lds_dwordx4 v[100:101], off
	s_add_u32 m0, s98, 0xe400
	s_nop 0
	global_load_lds_dwordx4 v[102:103], off
	v_lshl_add_u64 v[96:97], v[96:97], 0, 64
	v_lshl_add_u64 v[98:99], v[98:99], 0, 64
	v_lshl_add_u64 v[100:101], v[100:101], 0, 64
	v_lshl_add_u64 v[102:103], v[102:103], 0, 64
	s_waitcnt lgkmcnt(0)
	v_mfma_f32_32x32x16_bf16 v[48:63], v[64:67], v[72:75], v[48:63]
	ds_read_b128 v[80:83], v105 offset:0
	v_mfma_f32_32x32x16_bf16 v[32:47], v[64:67], v[76:79], v[32:47]
	ds_read_b128 v[84:87], v105 offset:2048
	v_mfma_f32_32x32x16_bf16 v[16:31], v[68:71], v[72:75], v[16:31]
	ds_read_b128 v[88:91], v107 offset:0
	v_mfma_f32_32x32x16_bf16 v[0:15], v[68:71], v[76:79], v[0:15]
	ds_read_b128 v[92:95], v107 offset:2048
	s_waitcnt vmcnt(8)
	s_waitcnt lgkmcnt(0)
	s_barrier
; template <bool BNN, class AL, class BL>
; __device__ __forceinline__ void gemm_tile(const AL& al, const BL& bl, int K, u16* smem, f32x16 (&acc)[2][2]) {
;     ...
;   G_LOAD(ra0, rb0, 0)
;   G_STORE(ra0, rb0, 0)
;   if (nkt > 1) G_LOAD(ra1, rb1, 1)
;   __syncthreads();
;   for (int kt = 0; kt < nkt; kt += 2) {
;     if (kt + 2 < nkt) G_LOAD(ra0, rb0, kt + 2)
;     G_COMPUTE(0)
;     if (kt + 1 < nkt) G_STORE(ra1, rb1, 1)
;     __syncthreads();
;     if (kt + 1 >= nkt) break;
;     if (kt + 3 < nkt) G_LOAD(ra1, rb1, kt + 3)
;     G_COMPUTE(1)
;     if (kt + 2 < nkt) G_STORE(ra0, rb0, 0)
;     __syncthreads();
;   }
	ds_read_b128 v[64:67], v104 offset:16384
	ds_read_b128 v[68:71], v104 offset:18432
	ds_read_b128 v[72:75], v106 offset:16384
	ds_read_b128 v[76:79], v106 offset:18432
	s_add_u32 m0, s98, 0x0
	v_mfma_f32_32x32x16_bf16 v[48:63], v[80:83], v[88:91], v[48:63]
	global_load_lds_dwordx4 v[96:97], off
	s_add_u32 m0, s98, 0x400
	v_mfma_f32_32x32x16_bf16 v[32:47], v[80:83], v[92:95], v[32:47]
	global_load_lds_dwordx4 v[98:99], off
	s_add_u32 m0, s98, 0x2000
	v_mfma_f32_32x32x16_bf16 v[16:31], v[84:87], v[88:91], v[16:31]
	global_load_lds_dwordx4 v[100:101], off
	s_add_u32 m0, s98, 0x2400
	v_mfma_f32_32x32x16_bf16 v[0:15], v[84:87], v[92:95], v[0:15]
	global_load_lds_dwordx4 v[102:103], off
	v_lshl_add_u64 v[96:97], v[96:97], 0, 64
	v_lshl_add_u64 v[98:99], v[98:99], 0, 64
	v_lshl_add_u64 v[100:101], v[100:101], 0, 64
	v_lshl_add_u64 v[102:103], v[102:103], 0, 64
	s_waitcnt lgkmcnt(0)
	v_mfma_f32_32x32x16_bf16 v[48:63], v[64:67], v[72:75], v[48:63]
	ds_read_b128 v[80:83], v105 offset:16384
	v_mfma_f32_32x32x16_bf16 v[32:47], v[64:67], v[76:79], v[32:47]
	ds_read_b128 v[84:87], v105 offset:18432
	v_mfma_f32_32x32x16_bf16 v[16:31], v[68:71], v[72:75], v[16:31]
	ds_read_b128 v[88:91], v107 offset:16384
	v_mfma_f32_32x32x16_bf16 v[0:15], v[68:71], v[76:79], v[0:15]
	ds_read_b128 v[92:95], v107 offset:18432
	s_waitcnt vmcnt(8)
	s_waitcnt lgkmcnt(0)
	s_barrier
	ds_read_b128 v[64:67], v104 offset:32768
	ds_read_b128 v[68:71], v104 offset:34816
	ds_read_b128 v[72:75], v106 offset:32768
	ds_read_b128 v[76:79], v106 offset:34816
	s_add_u32 m0, s98, 0x4000
	v_mfma_f32_32x32x16_bf16 v[48:63], v[80:83], v[88:91], v[48:63]
	global_load_lds_dwordx4 v[96:97], off
	s_add_u32 m0, s98, 0x4400
	v_mfma_f32_32x32x16_bf16 v[32:47], v[80:83], v[92:95], v[32:47]
	global_load_lds_dwordx4 v[98:99], off
	s_add_u32 m0, s98, 0x6000
	v_mfma_f32_32x32x16_bf16 v[16:31], v[84:87], v[88:91], v[16:31]
	global_load_lds_dwordx4 v[100:101], off
	s_add_u32 m0, s98, 0x6400
	v_mfma_f32_32x32x16_bf16 v[0:15], v[84:87], v[92:95], v[0:15]
	global_load_lds_dwordx4 v[102:103], off
	v_lshl_add_u64 v[96:97], v[96:97], 0, 64
	v_lshl_add_u64 v[98:99], v[98:99], 0, 64
	v_lshl_add_u64 v[100:101], v[100:101], 0, 64
	v_lshl_add_u64 v[102:103], v[102:103], 0, 64
	s_waitcnt lgkmcnt(0)
	v_mfma_f32_32x32x16_bf16 v[48:63], v[64:67], v[72:75], v[48:63]
	ds_read_b128 v[80:83], v105 offset:32768
	v_mfma_f32_32x32x16_bf16 v[32:47], v[64:67], v[76:79], v[32:47]
	ds_read_b128 v[84:87], v105 offset:34816
	v_mfma_f32_32x32x16_bf16 v[16:31], v[68:71], v[72:75], v[16:31]
	ds_read_b128 v[88:91], v107 offset:32768
	v_mfma_f32_32x32x16_bf16 v[0:15], v[68:71], v[76:79], v[0:15]
	ds_read_b128 v[92:95], v107 offset:34816
	s_waitcnt vmcnt(8)
	s_waitcnt lgkmcnt(0)
	s_barrier
	ds_read_b128 v[64:67], v104 offset:49152
	ds_read_b128 v[68:71], v104 offset:51200
	ds_read_b128 v[72:75], v106 offset:49152
	ds_read_b128 v[76:79], v106 offset:51200
	s_add_u32 m0, s98, 0x8000
	v_mfma_f32_32x32x16_bf16 v[48:63], v[80:83], v[88:91], v[48:63]
	global_load_lds_dwordx4 v[96:97], off
	s_add_u32 m0, s98, 0x8400
	v_mfma_f32_32x32x16_bf16 v[32:47], v[80:83], v[92:95], v[32:47]
	global_load_lds_dwordx4 v[98:99], off
	s_add_u32 m0, s98, 0xa000
	v_mfma_f32_32x32x16_bf16 v[16:31], v[84:87], v[88:91], v[16:31]
	global_load_lds_dwordx4 v[100:101], off
	s_add_u32 m0, s98, 0xa400
	v_mfma_f32_32x32x16_bf16 v[0:15], v[84:87], v[92:95], v[0:15]
	global_load_lds_dwordx4 v[102:103], off
	v_lshl_add_u64 v[96:97], v[96:97], 0, 64
	v_lshl_add_u64 v[98:99], v[98:99], 0, 64
	v_lshl_add_u64 v[100:101], v[100:101], 0, 64
	v_lshl_add_u64 v[102:103], v[102:103], 0, 64
	s_waitcnt lgkmcnt(0)
	v_mfma_f32_32x32x16_bf16 v[48:63], v[64:67], v[72:75], v[48:63]
	ds_read_b128 v[80:83], v105 offset:49152
	v_mfma_f32_32x32x16_bf16 v[32:47], v[64:67], v[76:79], v[32:47]
	ds_read_b128 v[84:87], v105 offset:51200
	v_mfma_f32_32x32x16_bf16 v[16:31], v[68:71], v[72:75], v[16:31]
	ds_read_b128 v[88:91], v107 offset:49152
	v_mfma_f32_32x32x16_bf16 v[0:15], v[68:71], v[76:79], v[0:15]
	ds_read_b128 v[92:95], v107 offset:51200
	s_waitcnt vmcnt(8)
	s_waitcnt lgkmcnt(0)
	s_mov_b32 s99, 6
.Lmy_pre_p0_loop:
	s_barrier
	ds_read_b128 v[64:67], v104 offset:0
	ds_read_b128 v[68:71], v104 offset:2048
	ds_read_b128 v[72:75], v106 offset:0
	ds_read_b128 v[76:79], v106 offset:2048
	s_add_u32 m0, s98, 0xc000
	v_mfma_f32_32x32x16_bf16 v[48:63], v[80:83], v[88:91], v[48:63]
	global_load_lds_dwordx4 v[96:97], off
	s_add_u32 m0, s98, 0xc400
	v_mfma_f32_32x32x16_bf16 v[32:47], v[80:83], v[92:95], v[32:47]
	global_load_lds_dwordx4 v[98:99], off
	s_add_u32 m0, s98, 0xe000
	v_mfma_f32_32x32x16_bf16 v[16:31], v[84:87], v[88:91], v[16:31]
	global_load_lds_dwordx4 v[100:101], off
	s_add_u32 m0, s98, 0xe400
	v_mfma_f32_32x32x16_bf16 v[0:15], v[84:87], v[92:95], v[0:15]
	global_load_lds_dwordx4 v[102:103], off
	v_lshl_add_u64 v[96:97], v[96:97], 0, 64
	v_lshl_add_u64 v[98:99], v[98:99], 0, 64
	v_lshl_add_u64 v[100:101], v[100:101], 0, 64
	v_lshl_add_u64 v[102:103], v[102:103], 0, 64
	s_waitcnt lgkmcnt(0)
	v_mfma_f32_32x32x16_bf16 v[48:63], v[64:67], v[72:75], v[48:63]
	ds_read_b128 v[80:83], v105 offset:0
	v_mfma_f32_32x32x16_bf16 v[32:47], v[64:67], v[76:79], v[32:47]
	ds_read_b128 v[84:87], v105 offset:2048
	v_mfma_f32_32x32x16_bf16 v[16:31], v[68:71], v[72:75], v[16:31]
	ds_read_b128 v[88:91], v107 offset:0
	v_mfma_f32_32x32x16_bf16 v[0:15], v[68:71], v[76:79], v[0:15]
	ds_read_b128 v[92:95], v107 offset:2048
	s_waitcnt vmcnt(8)
	s_waitcnt lgkmcnt(0)
	s_barrier
; template <bool BNN, class AL, class BL>
; __device__ __forceinline__ void gemm_tile(const AL& al, const BL& bl, int K, u16* smem, f32x16 (&acc)[2][2]) {
;     ...
;   for (int kt = 0; kt < nkt; kt += 2) {
;     if (kt + 2 < nkt) G_LOAD(ra0, rb0, kt + 2)
;     G_COMPUTE(0)
;     if (kt + 1 < nkt) G_STORE(ra1, rb1, 1)
;     __syncthreads();
;     if (kt + 1 >= nkt) break;
;     if (kt + 3 < nkt) G_LOAD(ra1, rb1, kt + 3)
;     G_COMPUTE(1)
;     if (kt + 2 < nkt) G_STORE(ra0, rb0, 0)
;     __syncthreads();
;   }
	ds_read_b128 v[64:67], v104 offset:16384
	ds_read_b128 v[68:71], v104 offset:18432
	ds_read_b128 v[72:75], v106 offset:16384
	ds_read_b128 v[76:79], v106 offset:18432
	s_add_u32 m0, s98, 0x0
	v_mfma_f32_32x32x16_bf16 v[48:63], v[80:83], v[88:91], v[48:63]
	global_load_lds_dwordx4 v[96:97], off
	s_add_u32 m0, s98, 0x400
	v_mfma_f32_32x32x16_bf16 v[32:47], v[80:83], v[92:95], v[32:47]
	global_load_lds_dwordx4 v[98:99], off
	s_add_u32 m0, s98, 0x2000
	v_mfma_f32_32x32x16_bf16 v[16:31], v[84:87], v[88:91], v[16:31]
	global_load_lds_dwordx4 v[100:101], off
	s_add_u32 m0, s98, 0x2400
	v_mfma_f32_32x32x16_bf16 v[0:15], v[84:87], v[92:95], v[0:15]
	global_load_lds_dwordx4 v[102:103], off
	v_lshl_add_u64 v[96:97], v[96:97], 0, 64
	v_lshl_add_u64 v[98:99], v[98:99], 0, 64
	v_lshl_add_u64 v[100:101], v[100:101], 0, 64
	v_lshl_add_u64 v[102:103], v[102:103], 0, 64
	s_waitcnt lgkmcnt(0)
	v_mfma_f32_32x32x16_bf16 v[48:63], v[64:67], v[72:75], v[48:63]
	ds_read_b128 v[80:83], v105 offset:16384
	v_mfma_f32_32x32x16_bf16 v[32:47], v[64:67], v[76:79], v[32:47]
	ds_read_b128 v[84:87], v105 offset:18432
	v_mfma_f32_32x32x16_bf16 v[16:31], v[68:71], v[72:75], v[16:31]
	ds_read_b128 v[88:91], v107 offset:16384
	v_mfma_f32_32x32x16_bf16 v[0:15], v[68:71], v[76:79], v[0:15]
	ds_read_b128 v[92:95], v107 offset:18432
	s_waitcnt vmcnt(8)
	s_waitcnt lgkmcnt(0)
	s_barrier
	ds_read_b128 v[64:67], v104 offset:32768
	ds_read_b128 v[68:71], v104 offset:34816
	ds_read_b128 v[72:75], v106 offset:32768
	ds_read_b128 v[76:79], v106 offset:34816
	s_add_u32 m0, s98, 0x4000
	v_mfma_f32_32x32x16_bf16 v[48:63], v[80:83], v[88:91], v[48:63]
	global_load_lds_dwordx4 v[96:97], off
	s_add_u32 m0, s98, 0x4400
	v_mfma_f32_32x32x16_bf16 v[32:47], v[80:83], v[92:95], v[32:47]
	global_load_lds_dwordx4 v[98:99], off
	s_add_u32 m0, s98, 0x6000
	v_mfma_f32_32x32x16_bf16 v[16:31], v[84:87], v[88:91], v[16:31]
	global_load_lds_dwordx4 v[100:101], off
	s_add_u32 m0, s98, 0x6400
	v_mfma_f32_32x32x16_bf16 v[0:15], v[84:87], v[92:95], v[0:15]
	global_load_lds_dwordx4 v[102:103], off
	v_lshl_add_u64 v[96:97], v[96:97], 0, 64
	v_lshl_add_u64 v[98:99], v[98:99], 0, 64
	v_lshl_add_u64 v[100:101], v[100:101], 0, 64
	v_lshl_add_u64 v[102:103], v[102:103], 0, 64
	s_waitcnt lgkmcnt(0)
	v_mfma_f32_32x32x16_bf16 v[48:63], v[64:67], v[72:75], v[48:63]
	ds_read_b128 v[80:83], v105 offset:32768
	v_mfma_f32_32x32x16_bf16 v[32:47], v[64:67], v[76:79], v[32:47]
	ds_read_b128 v[84:87], v105 offset:34816
	v_mfma_f32_32x32x16_bf16 v[16:31], v[68:71], v[72:75], v[16:31]
	ds_read_b128 v[88:91], v107 offset:32768
	v_mfma_f32_32x32x16_bf16 v[0:15], v[68:71], v[76:79], v[0:15]
	ds_read_b128 v[92:95], v107 offset:34816
	s_waitcnt vmcnt(8)
	s_waitcnt lgkmcnt(0)
	s_barrier
	ds_read_b128 v[64:67], v104 offset:49152
	ds_read_b128 v[68:71], v104 offset:51200
	ds_read_b128 v[72:75], v106 offset:49152
	ds_read_b128 v[76:79], v106 offset:51200
	s_add_u32 m0, s98, 0x8000
	v_mfma_f32_32x32x16_bf16 v[48:63], v[80:83], v[88:91], v[48:63]
	global_load_lds_dwordx4 v[96:97], off
	s_add_u32 m0, s98, 0x8400
	v_mfma_f32_32x32x16_bf16 v[32:47], v[80:83], v[92:95], v[32:47]
	global_load_lds_dwordx4 v[98:99], off
	s_add_u32 m0, s98, 0xa000
	v_mfma_f32_32x32x16_bf16 v[16:31], v[84:87], v[88:91], v[16:31]
	global_load_lds_dwordx4 v[100:101], off
	s_add_u32 m0, s98, 0xa400
	v_mfma_f32_32x32x16_bf16 v[0:15], v[84:87], v[92:95], v[0:15]
	global_load_lds_dwordx4 v[102:103], off
	v_lshl_add_u64 v[96:97], v[96:97], 0, 64
	v_lshl_add_u64 v[98:99], v[98:99], 0, 64
	v_lshl_add_u64 v[100:101], v[100:101], 0, 64
	v_lshl_add_u64 v[102:103], v[102:103], 0, 64
	s_waitcnt lgkmcnt(0)
	v_mfma_f32_32x32x16_bf16 v[48:63], v[64:67], v[72:75], v[48:63]
	ds_read_b128 v[80:83], v105 offset:49152
	v_mfma_f32_32x32x16_bf16 v[32:47], v[64:67], v[76:79], v[32:47]
	ds_read_b128 v[84:87], v105 offset:51200
	v_mfma_f32_32x32x16_bf16 v[16:31], v[68:71], v[72:75], v[16:31]
	ds_read_b128 v[88:91], v107 offset:49152
	v_mfma_f32_32x32x16_bf16 v[0:15], v[68:71], v[76:79], v[0:15]
	ds_read_b128 v[92:95], v107 offset:51200
	s_waitcnt vmcnt(8)
	s_waitcnt lgkmcnt(0)
	s_sub_u32 s99, s99, 1
	s_cmp_lg_u32 s99, 0
	s_cbranch_scc1 .Lmy_pre_p0_loop
	s_barrier
; template <bool BNN, class AL, class BL>
; __device__ __forceinline__ void gemm_tile(const AL& al, const BL& bl, int K, u16* smem, f32x16 (&acc)[2][2]) {
;     ...
;   for (int kt = 0; kt < nkt; kt += 2) {
;     if (kt + 2 < nkt) G_LOAD(ra0, rb0, kt + 2)
;     G_COMPUTE(0)
;     if (kt + 1 < nkt) G_STORE(ra1, rb1, 1)
;     __syncthreads();
;     if (kt + 1 >= nkt) break;
;     if (kt + 3 < nkt) G_LOAD(ra1, rb1, kt + 3)
;     G_COMPUTE(1)
;     if (kt + 2 < nkt) G_STORE(ra0, rb0, 0)
;     __syncthreads();
;   }
; __device__ __forceinline__ void gemm_nt_phase(const u16* A, int lda, const u16* Bt, int ldb, u16* C, int ldc,
;                               int Mt, int Nt, int K, int qcols, float qscale, u16* smem,
;                               u16* vtx = nullptr, u16* vtc = nullptr, u16* smv = nullptr) {
;     ...
;     __syncthreads();
;     Mt = 128;
;   }
;   const int nT = Mt * Nt;
;   for (int t = blockIdx.x; t < nT; t += gridDim.x) {
	ds_read_b128 v[64:67], v104 offset:0
	ds_read_b128 v[68:71], v104 offset:2048
	ds_read_b128 v[72:75], v106 offset:0
	ds_read_b128 v[76:79], v106 offset:2048
	s_add_u32 m0, s98, 0xc000
	v_mfma_f32_32x32x16_bf16 v[48:63], v[80:83], v[88:91], v[48:63]
	global_load_lds_dwordx4 v[96:97], off
	s_add_u32 m0, s98, 0xc400
	v_mfma_f32_32x32x16_bf16 v[32:47], v[80:83], v[92:95], v[32:47]
	global_load_lds_dwordx4 v[98:99], off
	s_add_u32 m0, s98, 0xe000
	v_mfma_f32_32x32x16_bf16 v[16:31], v[84:87], v[88:91], v[16:31]
	global_load_lds_dwordx4 v[100:101], off
	s_add_u32 m0, s98, 0xe400
	v_mfma_f32_32x32x16_bf16 v[0:15], v[84:87], v[92:95], v[0:15]
	global_load_lds_dwordx4 v[102:103], off
	v_lshl_add_u64 v[96:97], v[96:97], 0, 64
	v_lshl_add_u64 v[98:99], v[98:99], 0, 64
	v_lshl_add_u64 v[100:101], v[100:101], 0, 64
	v_lshl_add_u64 v[102:103], v[102:103], 0, 64
	s_waitcnt lgkmcnt(0)
	v_mfma_f32_32x32x16_bf16 v[48:63], v[64:67], v[72:75], v[48:63]
	ds_read_b128 v[80:83], v105 offset:0
	v_mfma_f32_32x32x16_bf16 v[32:47], v[64:67], v[76:79], v[32:47]
	ds_read_b128 v[84:87], v105 offset:2048
	v_mfma_f32_32x32x16_bf16 v[16:31], v[68:71], v[72:75], v[16:31]
	ds_read_b128 v[88:91], v107 offset:0
	v_mfma_f32_32x32x16_bf16 v[0:15], v[68:71], v[76:79], v[0:15]
	ds_read_b128 v[92:95], v107 offset:2048
	s_waitcnt vmcnt(8)
	s_waitcnt lgkmcnt(0)
	s_barrier
	ds_read_b128 v[64:67], v104 offset:16384
	ds_read_b128 v[68:71], v104 offset:18432
	ds_read_b128 v[72:75], v106 offset:16384
	ds_read_b128 v[76:79], v106 offset:18432
	v_mfma_f32_32x32x16_bf16 v[48:63], v[80:83], v[88:91], v[48:63]
	v_mfma_f32_32x32x16_bf16 v[32:47], v[80:83], v[92:95], v[32:47]
	v_mfma_f32_32x32x16_bf16 v[16:31], v[84:87], v[88:91], v[16:31]
	v_mfma_f32_32x32x16_bf16 v[0:15], v[84:87], v[92:95], v[0:15]
	s_waitcnt lgkmcnt(0)
	v_mfma_f32_32x32x16_bf16 v[48:63], v[64:67], v[72:75], v[48:63]
	ds_read_b128 v[80:83], v105 offset:16384
	v_mfma_f32_32x32x16_bf16 v[32:47], v[64:67], v[76:79], v[32:47]
	ds_read_b128 v[84:87], v105 offset:18432
	v_mfma_f32_32x32x16_bf16 v[16:31], v[68:71], v[72:75], v[16:31]
	ds_read_b128 v[88:91], v107 offset:16384
	v_mfma_f32_32x32x16_bf16 v[0:15], v[68:71], v[76:79], v[0:15]
	ds_read_b128 v[92:95], v107 offset:18432
	s_waitcnt vmcnt(4)
	s_waitcnt lgkmcnt(0)
	s_barrier
	ds_read_b128 v[64:67], v104 offset:32768
	ds_read_b128 v[68:71], v104 offset:34816
	ds_read_b128 v[72:75], v106 offset:32768
	ds_read_b128 v[76:79], v106 offset:34816
	v_mfma_f32_32x32x16_bf16 v[48:63], v[80:83], v[88:91], v[48:63]
	v_mfma_f32_32x32x16_bf16 v[32:47], v[80:83], v[92:95], v[32:47]
	v_mfma_f32_32x32x16_bf16 v[16:31], v[84:87], v[88:91], v[16:31]
	v_mfma_f32_32x32x16_bf16 v[0:15], v[84:87], v[92:95], v[0:15]
	s_waitcnt lgkmcnt(0)
	v_mfma_f32_32x32x16_bf16 v[48:63], v[64:67], v[72:75], v[48:63]
	ds_read_b128 v[80:83], v105 offset:32768
	v_mfma_f32_32x32x16_bf16 v[32:47], v[64:67], v[76:79], v[32:47]
	ds_read_b128 v[84:87], v105 offset:34816
	v_mfma_f32_32x32x16_bf16 v[16:31], v[68:71], v[72:75], v[16:31]
	ds_read_b128 v[88:91], v107 offset:32768
	v_mfma_f32_32x32x16_bf16 v[0:15], v[68:71], v[76:79], v[0:15]
	ds_read_b128 v[92:95], v107 offset:34816
	s_waitcnt vmcnt(0)
	s_waitcnt lgkmcnt(0)
	s_barrier
	ds_read_b128 v[64:67], v104 offset:49152
	ds_read_b128 v[68:71], v104 offset:51200
	ds_read_b128 v[72:75], v106 offset:49152
	ds_read_b128 v[76:79], v106 offset:51200
	v_mfma_f32_32x32x16_bf16 v[48:63], v[80:83], v[88:91], v[48:63]
	v_mfma_f32_32x32x16_bf16 v[32:47], v[80:83], v[92:95], v[32:47]
	v_mfma_f32_32x32x16_bf16 v[16:31], v[84:87], v[88:91], v[16:31]
	v_mfma_f32_32x32x16_bf16 v[0:15], v[84:87], v[92:95], v[0:15]
	s_waitcnt lgkmcnt(0)
	v_mfma_f32_32x32x16_bf16 v[48:63], v[64:67], v[72:75], v[48:63]
	ds_read_b128 v[80:83], v105 offset:49152
	v_mfma_f32_32x32x16_bf16 v[32:47], v[64:67], v[76:79], v[32:47]
	ds_read_b128 v[84:87], v105 offset:51200
	v_mfma_f32_32x32x16_bf16 v[16:31], v[68:71], v[72:75], v[16:31]
	ds_read_b128 v[88:91], v107 offset:49152
	v_mfma_f32_32x32x16_bf16 v[0:15], v[68:71], v[76:79], v[0:15]
	ds_read_b128 v[92:95], v107 offset:51200
	s_waitcnt lgkmcnt(0)
	v_mfma_f32_32x32x16_bf16 v[48:63], v[80:83], v[88:91], v[48:63]
	v_mfma_f32_32x32x16_bf16 v[32:47], v[80:83], v[92:95], v[32:47]
	v_mfma_f32_32x32x16_bf16 v[16:31], v[84:87], v[88:91], v[16:31]
	v_mfma_f32_32x32x16_bf16 v[0:15], v[84:87], v[92:95], v[0:15]
	s_nop 15
	s_barrier
	s_branch .LBB0_167
.LBB0_176:
	s_or_b64 exec, exec, s[0:1]
	s_movk_i32 s3, 0x300
	s_waitcnt vmcnt(63) expcnt(7) lgkmcnt(15)
	s_barrier
	s_cmp_ge_i32 s2, s3
	s_cbranch_scc0 .LBB0_178
	s_branch .LBB0_229

; template <bool BNN, class AL, class BL>
; __device__ __forceinline__ void gemm_tile(const AL& al, const BL& bl, int K, u16* smem, f32x16 (&acc)[2][2]) {
;     ...
;   G_LOAD(ra0, rb0, 0)
;   G_STORE(ra0, rb0, 0)
;   if (nkt > 1) G_LOAD(ra1, rb1, 1)
;   __syncthreads();
; __device__ __forceinline__ void gemm_nt_phase(const u16* A, int lda, const u16* Bt, int ldb, u16* C, int ldc,
;                               int Mt, int Nt, int K, int qcols, float qscale, u16* smem,
;                               u16* vtx = nullptr, u16* vtc = nullptr, u16* smv = nullptr) {
;     ...
;     for (int t = VBID; t < nS; t += VGRID) {
;       const int ms = t / NtS, ns = t - ms * NtS;
;       const u16* Ab = A + (long)(N_X + ms * 128) * lda;
;       const u16* Bb = Bt + (long)ns * 128 * ldb;
;       auto al = [=](int r, int k) { return ldg16(Ab + (unsigned)(r * lda + k)); };
;       auto bl = [=](int r, int k) { return ldg16(Bb + (unsigned)(r * ldb + k)); };
;       f32x16 acc[2][2];
;       gemm_tile<false>(al, bl, K, smv, acc);
.LBB0_808:
	s_waitcnt vmcnt(0)
	s_barrier
	v_readfirstlane_b32 s98, v153
	v_bfe_u32 v108, v152, 6, 2
	v_readlane_b32 s100, v252, 0
	v_readlane_b32 s101, v252, 1
	v_readfirstlane_b32 s99, v108
	s_nop 3
	s_sub_u32 s100, s100, 0x170
	s_subb_u32 s101, s101, 0
	s_lshl_b32 vcc_lo, s2, 1
	s_add_u32 vcc_lo, vcc_lo, s98
	s_lshr_b32 vcc_hi, vcc_lo, 3
	s_and_b32 vcc_lo, vcc_lo, 7
	v_mul_u32_u24_e32 v108, 0x12000, v153
	v_add_u32_e32 v108, 16, v108
	v_and_b32_e32 v109, 31, v152
	v_bfe_u32 v110, v152, 2, 2
	v_bfe_u32 v111, v152, 5, 1
	v_xor_b32_e32 v112, v111, v110
	v_lshlrev_b32_e32 v112, 4, v112
	v_xor_b32_e32 v113, 32, v112
	v_bfe_u32 v114, v152, 7, 1
	v_lshl_add_u32 v114, v114, 6, v109
	v_lshl_add_u32 v114, v114, 6, v108
	v_bfe_u32 v115, v152, 6, 1
	v_lshl_add_u32 v115, v115, 6, v109
	v_lshl_add_u32 v115, v115, 6, v108
	v_add_u32_e32 v104, v114, v112
	v_add_u32_e32 v105, v114, v113
	v_add_u32_e32 v115, 0x2000, v115
	v_add_u32_e32 v106, v115, v112
	v_add_u32_e32 v107, v115, v113
	v_bfe_u32 v109, v152, 2, 4
	v_bfe_u32 v110, v152, 4, 2
	v_and_b32_e32 v111, 3, v152
	v_xor_b32_e32 v110, v111, v110
	v_bfe_u32 v111, v152, 6, 2
	v_lshl_add_u32 v109, v111, 5, v109
	s_mov_b32 m0, 0x800
	v_mul_lo_u32 v112, v109, m0
	v_lshl_add_u32 v112, v110, 4, v112
	s_lshl_b32 s98, s98, 0
	s_mov_b32 s99, s99
	s_lshl_b32 vcc_hi, vcc_hi, 8
	s_or_b32 s98, s98, vcc_hi
	s_lshl_b32 vcc_lo, vcc_lo, 16
	s_or_b32 s98, s98, vcc_lo
	s_load_dwordx2 s[100:101], s[100:101], 0x158
	s_bfe_u32 m0, s98, 0x80008
	s_lshl_b32 m0, m0, 7
	s_add_u32 m0, m0, 0x8000
	s_mul_i32 m0, m0, 0x800
	s_waitcnt lgkmcnt(0)
	s_add_u32 s100, s100, m0
	s_addc_u32 s101, s101, 0
	v_mov_b32_e32 v113, s101
	v_add_co_u32_e32 v96, vcc, s100, v112
	s_nop 1
	v_addc_co_u32_e32 v97, vcc, 0, v113, vcc
	v_add_co_u32_e32 v98, vcc, 0x8000, v96
	s_nop 1
	v_addc_co_u32_e32 v99, vcc, 0, v97, vcc
	v_readlane_b32 s100, v252, 0
	v_readlane_b32 s101, v252, 1
	s_nop 3
	s_sub_u32 s100, s100, 0x170
	s_subb_u32 s101, s101, 0
	s_load_dwordx2 s[100:101], s[100:101], 0xd8
	s_bfe_u32 m0, s98, 0x80010
	s_lshl_b32 m0, m0, 7
	s_mul_i32 m0, m0, 0x800
	s_waitcnt lgkmcnt(0)
	s_add_u32 s100, s100, m0
	s_addc_u32 s101, s101, 0
	v_mov_b32_e32 v113, s101
	v_add_co_u32_e32 v100, vcc, s100, v112
	s_nop 1
	v_addc_co_u32_e32 v101, vcc, 0, v113, vcc
	v_add_co_u32_e32 v102, vcc, 0x8000, v100
	s_nop 1
	v_addc_co_u32_e32 v103, vcc, 0, v101, vcc
	s_and_b32 m0, s98, 1
	s_mul_i32 m0, m0, 0x12000
	s_lshl_b32 s99, s99, 11
	s_add_u32 s98, m0, s99
	s_add_u32 s98, s98, 16
	s_add_u32 m0, s98, 0x0
	s_nop 0
	global_load_lds_dwordx4 v[96:97], off
	s_add_u32 m0, s98, 0x400
	s_nop 0
	global_load_lds_dwordx4 v[98:99], off
	s_add_u32 m0, s98, 0x2000
	s_nop 0
	global_load_lds_dwordx4 v[100:101], off
	s_add_u32 m0, s98, 0x2400
	s_nop 0
	global_load_lds_dwordx4 v[102:103], off
	v_lshl_add_u64 v[96:97], v[96:97], 0, 64
	v_lshl_add_u64 v[98:99], v[98:99], 0, 64
	v_lshl_add_u64 v[100:101], v[100:101], 0, 64
	v_lshl_add_u64 v[102:103], v[102:103], 0, 64
	s_add_u32 m0, s98, 0x4000
	s_nop 0
	global_load_lds_dwordx4 v[96:97], off
	s_add_u32 m0, s98, 0x4400
	s_nop 0
	global_load_lds_dwordx4 v[98:99], off
	s_add_u32 m0, s98, 0x6000
	s_nop 0
	global_load_lds_dwordx4 v[100:101], off
	s_add_u32 m0, s98, 0x6400
	s_nop 0
	global_load_lds_dwordx4 v[102:103], off
	v_lshl_add_u64 v[96:97], v[96:97], 0, 64
	v_lshl_add_u64 v[98:99], v[98:99], 0, 64
	v_lshl_add_u64 v[100:101], v[100:101], 0, 64
	v_lshl_add_u64 v[102:103], v[102:103], 0, 64
	s_add_u32 m0, s98, 0x8000
	s_nop 0
	global_load_lds_dwordx4 v[96:97], off
	s_add_u32 m0, s98, 0x8400
	s_nop 0
	global_load_lds_dwordx4 v[98:99], off
	s_add_u32 m0, s98, 0xa000
	s_nop 0
	global_load_lds_dwordx4 v[100:101], off
	s_add_u32 m0, s98, 0xa400
	s_nop 0
	global_load_lds_dwordx4 v[102:103], off
	v_lshl_add_u64 v[96:97], v[96:97], 0, 64
	v_lshl_add_u64 v[98:99], v[98:99], 0, 64
	v_lshl_add_u64 v[100:101], v[100:101], 0, 64
	v_lshl_add_u64 v[102:103], v[102:103], 0, 64
	s_waitcnt vmcnt(8)
	s_barrier
	ds_read_b128 v[64:67], v104 offset:0
	ds_read_b128 v[68:71], v104 offset:2048
	ds_read_b128 v[72:75], v106 offset:0
	ds_read_b128 v[76:79], v106 offset:2048
	s_add_u32 m0, s98, 0xc000
	s_nop 0
	global_load_lds_dwordx4 v[96:97], off
	s_add_u32 m0, s98, 0xc400
	s_nop 0
	global_load_lds_dwordx4 v[98:99], off
	s_add_u32 m0, s98, 0xe000
	s_nop 0
	global_load_lds_dwordx4 v[100:101], off
	s_add_u32 m0, s98, 0xe400
	s_nop 0
	global_load_lds_dwordx4 v[102:103], off
	v_lshl_add_u64 v[96:97], v[96:97], 0, 64
	v_lshl_add_u64 v[98:99], v[98:99], 0, 64
	v_lshl_add_u64 v[100:101], v[100:101], 0, 64
	v_lshl_add_u64 v[102:103], v[102:103], 0, 64
	s_waitcnt lgkmcnt(0)
	v_mfma_f32_32x32x16_bf16 v[48:63], v[64:67], v[72:75], v[48:63]
	ds_read_b128 v[80:83], v105 offset:0
	v_mfma_f32_32x32x16_bf16 v[32:47], v[64:67], v[76:79], v[32:47]
	ds_read_b128 v[84:87], v105 offset:2048
	v_mfma_f32_32x32x16_bf16 v[16:31], v[68:71], v[72:75], v[16:31]
	ds_read_b128 v[88:91], v107 offset:0
	v_mfma_f32_32x32x16_bf16 v[0:15], v[68:71], v[76:79], v[0:15]
	ds_read_b128 v[92:95], v107 offset:2048
	s_waitcnt vmcnt(8)
	s_waitcnt lgkmcnt(0)
	s_barrier
; template <bool BNN, class AL, class BL>
; __device__ __forceinline__ void gemm_tile(const AL& al, const BL& bl, int K, u16* smem, f32x16 (&acc)[2][2]) {
;     ...
;   for (int kt = 0; kt < nkt; kt += 2) {
;     if (kt + 2 < nkt) G_LOAD(ra0, rb0, kt + 2)
;     G_COMPUTE(0)
;     if (kt + 1 < nkt) G_STORE(ra1, rb1, 1)
;     __syncthreads();
;     if (kt + 1 >= nkt) break;
;     if (kt + 3 < nkt) G_LOAD(ra1, rb1, kt + 3)
;     G_COMPUTE(1)
;     if (kt + 2 < nkt) G_STORE(ra0, rb0, 0)
;     __syncthreads();
;   }
	ds_read_b128 v[64:67], v104 offset:16384
	ds_read_b128 v[68:71], v104 offset:18432
	ds_read_b128 v[72:75], v106 offset:16384
	ds_read_b128 v[76:79], v106 offset:18432
	s_add_u32 m0, s98, 0x0
	v_mfma_f32_32x32x16_bf16 v[48:63], v[80:83], v[88:91], v[48:63]
	global_load_lds_dwordx4 v[96:97], off
	s_add_u32 m0, s98, 0x400
	v_mfma_f32_32x32x16_bf16 v[32:47], v[80:83], v[92:95], v[32:47]
	global_load_lds_dwordx4 v[98:99], off
	s_add_u32 m0, s98, 0x2000
	v_mfma_f32_32x32x16_bf16 v[16:31], v[84:87], v[88:91], v[16:31]
	global_load_lds_dwordx4 v[100:101], off
	s_add_u32 m0, s98, 0x2400
	v_mfma_f32_32x32x16_bf16 v[0:15], v[84:87], v[92:95], v[0:15]
	global_load_lds_dwordx4 v[102:103], off
	v_lshl_add_u64 v[96:97], v[96:97], 0, 64
	v_lshl_add_u64 v[98:99], v[98:99], 0, 64
	v_lshl_add_u64 v[100:101], v[100:101], 0, 64
	v_lshl_add_u64 v[102:103], v[102:103], 0, 64
	s_waitcnt lgkmcnt(0)
	v_mfma_f32_32x32x16_bf16 v[48:63], v[64:67], v[72:75], v[48:63]
	ds_read_b128 v[80:83], v105 offset:16384
	v_mfma_f32_32x32x16_bf16 v[32:47], v[64:67], v[76:79], v[32:47]
	ds_read_b128 v[84:87], v105 offset:18432
	v_mfma_f32_32x32x16_bf16 v[16:31], v[68:71], v[72:75], v[16:31]
	ds_read_b128 v[88:91], v107 offset:16384
	v_mfma_f32_32x32x16_bf16 v[0:15], v[68:71], v[76:79], v[0:15]
	ds_read_b128 v[92:95], v107 offset:18432
	s_waitcnt vmcnt(8)
	s_waitcnt lgkmcnt(0)
	s_barrier
	ds_read_b128 v[64:67], v104 offset:32768
	ds_read_b128 v[68:71], v104 offset:34816
	ds_read_b128 v[72:75], v106 offset:32768
	ds_read_b128 v[76:79], v106 offset:34816
	s_add_u32 m0, s98, 0x4000
	v_mfma_f32_32x32x16_bf16 v[48:63], v[80:83], v[88:91], v[48:63]
	global_load_lds_dwordx4 v[96:97], off
	s_add_u32 m0, s98, 0x4400
	v_mfma_f32_32x32x16_bf16 v[32:47], v[80:83], v[92:95], v[32:47]
	global_load_lds_dwordx4 v[98:99], off
	s_add_u32 m0, s98, 0x6000
	v_mfma_f32_32x32x16_bf16 v[16:31], v[84:87], v[88:91], v[16:31]
	global_load_lds_dwordx4 v[100:101], off
	s_add_u32 m0, s98, 0x6400
	v_mfma_f32_32x32x16_bf16 v[0:15], v[84:87], v[92:95], v[0:15]
	global_load_lds_dwordx4 v[102:103], off
	v_lshl_add_u64 v[96:97], v[96:97], 0, 64
	v_lshl_add_u64 v[98:99], v[98:99], 0, 64
	v_lshl_add_u64 v[100:101], v[100:101], 0, 64
	v_lshl_add_u64 v[102:103], v[102:103], 0, 64
	s_waitcnt lgkmcnt(0)
	v_mfma_f32_32x32x16_bf16 v[48:63], v[64:67], v[72:75], v[48:63]
	ds_read_b128 v[80:83], v105 offset:32768
	v_mfma_f32_32x32x16_bf16 v[32:47], v[64:67], v[76:79], v[32:47]
	ds_read_b128 v[84:87], v105 offset:34816
	v_mfma_f32_32x32x16_bf16 v[16:31], v[68:71], v[72:75], v[16:31]
	ds_read_b128 v[88:91], v107 offset:32768
	v_mfma_f32_32x32x16_bf16 v[0:15], v[68:71], v[76:79], v[0:15]
	ds_read_b128 v[92:95], v107 offset:34816
	s_waitcnt vmcnt(8)
	s_waitcnt lgkmcnt(0)
	s_barrier
	ds_read_b128 v[64:67], v104 offset:49152
	ds_read_b128 v[68:71], v104 offset:51200
	ds_read_b128 v[72:75], v106 offset:49152
	ds_read_b128 v[76:79], v106 offset:51200
	s_add_u32 m0, s98, 0x8000
	v_mfma_f32_32x32x16_bf16 v[48:63], v[80:83], v[88:91], v[48:63]
	global_load_lds_dwordx4 v[96:97], off
	s_add_u32 m0, s98, 0x8400
	v_mfma_f32_32x32x16_bf16 v[32:47], v[80:83], v[92:95], v[32:47]
	global_load_lds_dwordx4 v[98:99], off
	s_add_u32 m0, s98, 0xa000
	v_mfma_f32_32x32x16_bf16 v[16:31], v[84:87], v[88:91], v[16:31]
	global_load_lds_dwordx4 v[100:101], off
	s_add_u32 m0, s98, 0xa400
	v_mfma_f32_32x32x16_bf16 v[0:15], v[84:87], v[92:95], v[0:15]
	global_load_lds_dwordx4 v[102:103], off
	v_lshl_add_u64 v[96:97], v[96:97], 0, 64
	v_lshl_add_u64 v[98:99], v[98:99], 0, 64
	v_lshl_add_u64 v[100:101], v[100:101], 0, 64
	v_lshl_add_u64 v[102:103], v[102:103], 0, 64
	s_waitcnt lgkmcnt(0)
	v_mfma_f32_32x32x16_bf16 v[48:63], v[64:67], v[72:75], v[48:63]
	ds_read_b128 v[80:83], v105 offset:49152
	v_mfma_f32_32x32x16_bf16 v[32:47], v[64:67], v[76:79], v[32:47]
	ds_read_b128 v[84:87], v105 offset:51200
	v_mfma_f32_32x32x16_bf16 v[16:31], v[68:71], v[72:75], v[16:31]
	ds_read_b128 v[88:91], v107 offset:49152
	v_mfma_f32_32x32x16_bf16 v[0:15], v[68:71], v[76:79], v[0:15]
	ds_read_b128 v[92:95], v107 offset:51200
	s_waitcnt vmcnt(8)
	s_waitcnt lgkmcnt(0)
	s_mov_b32 s99, 6
.Lmy_pre_p1_loop:
	s_barrier
	ds_read_b128 v[64:67], v104 offset:0
	ds_read_b128 v[68:71], v104 offset:2048
	ds_read_b128 v[72:75], v106 offset:0
	ds_read_b128 v[76:79], v106 offset:2048
	s_add_u32 m0, s98, 0xc000
	v_mfma_f32_32x32x16_bf16 v[48:63], v[80:83], v[88:91], v[48:63]
	global_load_lds_dwordx4 v[96:97], off
	s_add_u32 m0, s98, 0xc400
	v_mfma_f32_32x32x16_bf16 v[32:47], v[80:83], v[92:95], v[32:47]
	global_load_lds_dwordx4 v[98:99], off
	s_add_u32 m0, s98, 0xe000
	v_mfma_f32_32x32x16_bf16 v[16:31], v[84:87], v[88:91], v[16:31]
	global_load_lds_dwordx4 v[100:101], off
	s_add_u32 m0, s98, 0xe400
	v_mfma_f32_32x32x16_bf16 v[0:15], v[84:87], v[92:95], v[0:15]
	global_load_lds_dwordx4 v[102:103], off
	v_lshl_add_u64 v[96:97], v[96:97], 0, 64
	v_lshl_add_u64 v[98:99], v[98:99], 0, 64
	v_lshl_add_u64 v[100:101], v[100:101], 0, 64
	v_lshl_add_u64 v[102:103], v[102:103], 0, 64
	s_waitcnt lgkmcnt(0)
	v_mfma_f32_32x32x16_bf16 v[48:63], v[64:67], v[72:75], v[48:63]
	ds_read_b128 v[80:83], v105 offset:0
	v_mfma_f32_32x32x16_bf16 v[32:47], v[64:67], v[76:79], v[32:47]
	ds_read_b128 v[84:87], v105 offset:2048
	v_mfma_f32_32x32x16_bf16 v[16:31], v[68:71], v[72:75], v[16:31]
	ds_read_b128 v[88:91], v107 offset:0
	v_mfma_f32_32x32x16_bf16 v[0:15], v[68:71], v[76:79], v[0:15]
	ds_read_b128 v[92:95], v107 offset:2048
	s_waitcnt vmcnt(8)
	s_waitcnt lgkmcnt(0)
	s_barrier
; template <bool BNN, class AL, class BL>
; __device__ __forceinline__ void gemm_tile(const AL& al, const BL& bl, int K, u16* smem, f32x16 (&acc)[2][2]) {
;     ...
;   for (int kt = 0; kt < nkt; kt += 2) {
;     if (kt + 2 < nkt) G_LOAD(ra0, rb0, kt + 2)
;     G_COMPUTE(0)
;     if (kt + 1 < nkt) G_STORE(ra1, rb1, 1)
;     __syncthreads();
;     if (kt + 1 >= nkt) break;
;     if (kt + 3 < nkt) G_LOAD(ra1, rb1, kt + 3)
;     G_COMPUTE(1)
;     if (kt + 2 < nkt) G_STORE(ra0, rb0, 0)
;     __syncthreads();
;   }
	ds_read_b128 v[64:67], v104 offset:16384
	ds_read_b128 v[68:71], v104 offset:18432
	ds_read_b128 v[72:75], v106 offset:16384
	ds_read_b128 v[76:79], v106 offset:18432
	s_add_u32 m0, s98, 0x0
	v_mfma_f32_32x32x16_bf16 v[48:63], v[80:83], v[88:91], v[48:63]
	global_load_lds_dwordx4 v[96:97], off
	s_add_u32 m0, s98, 0x400
	v_mfma_f32_32x32x16_bf16 v[32:47], v[80:83], v[92:95], v[32:47]
	global_load_lds_dwordx4 v[98:99], off
	s_add_u32 m0, s98, 0x2000
	v_mfma_f32_32x32x16_bf16 v[16:31], v[84:87], v[88:91], v[16:31]
	global_load_lds_dwordx4 v[100:101], off
	s_add_u32 m0, s98, 0x2400
	v_mfma_f32_32x32x16_bf16 v[0:15], v[84:87], v[92:95], v[0:15]
	global_load_lds_dwordx4 v[102:103], off
	v_lshl_add_u64 v[96:97], v[96:97], 0, 64
	v_lshl_add_u64 v[98:99], v[98:99], 0, 64
	v_lshl_add_u64 v[100:101], v[100:101], 0, 64
	v_lshl_add_u64 v[102:103], v[102:103], 0, 64
	s_waitcnt lgkmcnt(0)
	v_mfma_f32_32x32x16_bf16 v[48:63], v[64:67], v[72:75], v[48:63]
	ds_read_b128 v[80:83], v105 offset:16384
	v_mfma_f32_32x32x16_bf16 v[32:47], v[64:67], v[76:79], v[32:47]
	ds_read_b128 v[84:87], v105 offset:18432
	v_mfma_f32_32x32x16_bf16 v[16:31], v[68:71], v[72:75], v[16:31]
	ds_read_b128 v[88:91], v107 offset:16384
	v_mfma_f32_32x32x16_bf16 v[0:15], v[68:71], v[76:79], v[0:15]
	ds_read_b128 v[92:95], v107 offset:18432
	s_waitcnt vmcnt(8)
	s_waitcnt lgkmcnt(0)
	s_barrier
	ds_read_b128 v[64:67], v104 offset:32768
	ds_read_b128 v[68:71], v104 offset:34816
	ds_read_b128 v[72:75], v106 offset:32768
	ds_read_b128 v[76:79], v106 offset:34816
	s_add_u32 m0, s98, 0x4000
	v_mfma_f32_32x32x16_bf16 v[48:63], v[80:83], v[88:91], v[48:63]
	global_load_lds_dwordx4 v[96:97], off
	s_add_u32 m0, s98, 0x4400
	v_mfma_f32_32x32x16_bf16 v[32:47], v[80:83], v[92:95], v[32:47]
	global_load_lds_dwordx4 v[98:99], off
	s_add_u32 m0, s98, 0x6000
	v_mfma_f32_32x32x16_bf16 v[16:31], v[84:87], v[88:91], v[16:31]
	global_load_lds_dwordx4 v[100:101], off
	s_add_u32 m0, s98, 0x6400
	v_mfma_f32_32x32x16_bf16 v[0:15], v[84:87], v[92:95], v[0:15]
	global_load_lds_dwordx4 v[102:103], off
	v_lshl_add_u64 v[96:97], v[96:97], 0, 64
	v_lshl_add_u64 v[98:99], v[98:99], 0, 64
	v_lshl_add_u64 v[100:101], v[100:101], 0, 64
	v_lshl_add_u64 v[102:103], v[102:103], 0, 64
	s_waitcnt lgkmcnt(0)
	v_mfma_f32_32x32x16_bf16 v[48:63], v[64:67], v[72:75], v[48:63]
	ds_read_b128 v[80:83], v105 offset:32768
	v_mfma_f32_32x32x16_bf16 v[32:47], v[64:67], v[76:79], v[32:47]
	ds_read_b128 v[84:87], v105 offset:34816
	v_mfma_f32_32x32x16_bf16 v[16:31], v[68:71], v[72:75], v[16:31]
	ds_read_b128 v[88:91], v107 offset:32768
	v_mfma_f32_32x32x16_bf16 v[0:15], v[68:71], v[76:79], v[0:15]
	ds_read_b128 v[92:95], v107 offset:34816
	s_waitcnt vmcnt(8)
	s_waitcnt lgkmcnt(0)
	s_barrier
	ds_read_b128 v[64:67], v104 offset:49152
	ds_read_b128 v[68:71], v104 offset:51200
	ds_read_b128 v[72:75], v106 offset:49152
	ds_read_b128 v[76:79], v106 offset:51200
	s_add_u32 m0, s98, 0x8000
	v_mfma_f32_32x32x16_bf16 v[48:63], v[80:83], v[88:91], v[48:63]
	global_load_lds_dwordx4 v[96:97], off
	s_add_u32 m0, s98, 0x8400
	v_mfma_f32_32x32x16_bf16 v[32:47], v[80:83], v[92:95], v[32:47]
	global_load_lds_dwordx4 v[98:99], off
	s_add_u32 m0, s98, 0xa000
	v_mfma_f32_32x32x16_bf16 v[16:31], v[84:87], v[88:91], v[16:31]
	global_load_lds_dwordx4 v[100:101], off
	s_add_u32 m0, s98, 0xa400
	v_mfma_f32_32x32x16_bf16 v[0:15], v[84:87], v[92:95], v[0:15]
	global_load_lds_dwordx4 v[102:103], off
	v_lshl_add_u64 v[96:97], v[96:97], 0, 64
	v_lshl_add_u64 v[98:99], v[98:99], 0, 64
	v_lshl_add_u64 v[100:101], v[100:101], 0, 64
	v_lshl_add_u64 v[102:103], v[102:103], 0, 64
	s_waitcnt lgkmcnt(0)
	v_mfma_f32_32x32x16_bf16 v[48:63], v[64:67], v[72:75], v[48:63]
	ds_read_b128 v[80:83], v105 offset:49152
	v_mfma_f32_32x32x16_bf16 v[32:47], v[64:67], v[76:79], v[32:47]
	ds_read_b128 v[84:87], v105 offset:51200
	v_mfma_f32_32x32x16_bf16 v[16:31], v[68:71], v[72:75], v[16:31]
	ds_read_b128 v[88:91], v107 offset:49152
	v_mfma_f32_32x32x16_bf16 v[0:15], v[68:71], v[76:79], v[0:15]
	ds_read_b128 v[92:95], v107 offset:51200
	s_waitcnt vmcnt(8)
	s_waitcnt lgkmcnt(0)
	s_sub_u32 s99, s99, 1
	s_cmp_lg_u32 s99, 0
	s_cbranch_scc1 .Lmy_pre_p1_loop
	s_barrier
; template <bool BNN, class AL, class BL>
; __device__ __forceinline__ void gemm_tile(const AL& al, const BL& bl, int K, u16* smem, f32x16 (&acc)[2][2]) {
;     ...
;   for (int kt = 0; kt < nkt; kt += 2) {
;     if (kt + 2 < nkt) G_LOAD(ra0, rb0, kt + 2)
;     G_COMPUTE(0)
;     if (kt + 1 < nkt) G_STORE(ra1, rb1, 1)
;     __syncthreads();
;     if (kt + 1 >= nkt) break;
;     if (kt + 3 < nkt) G_LOAD(ra1, rb1, kt + 3)
;     G_COMPUTE(1)
;     if (kt + 2 < nkt) G_STORE(ra0, rb0, 0)
;     __syncthreads();
;   }
; __device__ __forceinline__ void gemm_nt_phase(const u16* A, int lda, const u16* Bt, int ldb, u16* C, int ldc,
;                               int Mt, int Nt, int K, int qcols, float qscale, u16* smem,
;                               u16* vtx = nullptr, u16* vtc = nullptr, u16* smv = nullptr) {
;     ...
;     __syncthreads();
;     Mt = 128;
;   }
;   const int nT = Mt * Nt;
;   for (int t = blockIdx.x; t < nT; t += gridDim.x) {
	ds_read_b128 v[64:67], v104 offset:0
	ds_read_b128 v[68:71], v104 offset:2048
	ds_read_b128 v[72:75], v106 offset:0
	ds_read_b128 v[76:79], v106 offset:2048
	s_add_u32 m0, s98, 0xc000
	v_mfma_f32_32x32x16_bf16 v[48:63], v[80:83], v[88:91], v[48:63]
	global_load_lds_dwordx4 v[96:97], off
	s_add_u32 m0, s98, 0xc400
	v_mfma_f32_32x32x16_bf16 v[32:47], v[80:83], v[92:95], v[32:47]
	global_load_lds_dwordx4 v[98:99], off
	s_add_u32 m0, s98, 0xe000
	v_mfma_f32_32x32x16_bf16 v[16:31], v[84:87], v[88:91], v[16:31]
	global_load_lds_dwordx4 v[100:101], off
	s_add_u32 m0, s98, 0xe400
	v_mfma_f32_32x32x16_bf16 v[0:15], v[84:87], v[92:95], v[0:15]
	global_load_lds_dwordx4 v[102:103], off
	v_lshl_add_u64 v[96:97], v[96:97], 0, 64
	v_lshl_add_u64 v[98:99], v[98:99], 0, 64
	v_lshl_add_u64 v[100:101], v[100:101], 0, 64
	v_lshl_add_u64 v[102:103], v[102:103], 0, 64
	s_waitcnt lgkmcnt(0)
	v_mfma_f32_32x32x16_bf16 v[48:63], v[64:67], v[72:75], v[48:63]
	ds_read_b128 v[80:83], v105 offset:0
	v_mfma_f32_32x32x16_bf16 v[32:47], v[64:67], v[76:79], v[32:47]
	ds_read_b128 v[84:87], v105 offset:2048
	v_mfma_f32_32x32x16_bf16 v[16:31], v[68:71], v[72:75], v[16:31]
	ds_read_b128 v[88:91], v107 offset:0
	v_mfma_f32_32x32x16_bf16 v[0:15], v[68:71], v[76:79], v[0:15]
	ds_read_b128 v[92:95], v107 offset:2048
	s_waitcnt vmcnt(8)
	s_waitcnt lgkmcnt(0)
	s_barrier
	ds_read_b128 v[64:67], v104 offset:16384
	ds_read_b128 v[68:71], v104 offset:18432
	ds_read_b128 v[72:75], v106 offset:16384
	ds_read_b128 v[76:79], v106 offset:18432
	v_mfma_f32_32x32x16_bf16 v[48:63], v[80:83], v[88:91], v[48:63]
	v_mfma_f32_32x32x16_bf16 v[32:47], v[80:83], v[92:95], v[32:47]
	v_mfma_f32_32x32x16_bf16 v[16:31], v[84:87], v[88:91], v[16:31]
	v_mfma_f32_32x32x16_bf16 v[0:15], v[84:87], v[92:95], v[0:15]
	s_waitcnt lgkmcnt(0)
	v_mfma_f32_32x32x16_bf16 v[48:63], v[64:67], v[72:75], v[48:63]
	ds_read_b128 v[80:83], v105 offset:16384
	v_mfma_f32_32x32x16_bf16 v[32:47], v[64:67], v[76:79], v[32:47]
	ds_read_b128 v[84:87], v105 offset:18432
	v_mfma_f32_32x32x16_bf16 v[16:31], v[68:71], v[72:75], v[16:31]
	ds_read_b128 v[88:91], v107 offset:16384
	v_mfma_f32_32x32x16_bf16 v[0:15], v[68:71], v[76:79], v[0:15]
	ds_read_b128 v[92:95], v107 offset:18432
	s_waitcnt vmcnt(4)
	s_waitcnt lgkmcnt(0)
	s_barrier
	ds_read_b128 v[64:67], v104 offset:32768
	ds_read_b128 v[68:71], v104 offset:34816
	ds_read_b128 v[72:75], v106 offset:32768
	ds_read_b128 v[76:79], v106 offset:34816
	v_mfma_f32_32x32x16_bf16 v[48:63], v[80:83], v[88:91], v[48:63]
	v_mfma_f32_32x32x16_bf16 v[32:47], v[80:83], v[92:95], v[32:47]
	v_mfma_f32_32x32x16_bf16 v[16:31], v[84:87], v[88:91], v[16:31]
	v_mfma_f32_32x32x16_bf16 v[0:15], v[84:87], v[92:95], v[0:15]
	s_waitcnt lgkmcnt(0)
	v_mfma_f32_32x32x16_bf16 v[48:63], v[64:67], v[72:75], v[48:63]
	ds_read_b128 v[80:83], v105 offset:32768
	v_mfma_f32_32x32x16_bf16 v[32:47], v[64:67], v[76:79], v[32:47]
	ds_read_b128 v[84:87], v105 offset:34816
	v_mfma_f32_32x32x16_bf16 v[16:31], v[68:71], v[72:75], v[16:31]
	ds_read_b128 v[88:91], v107 offset:32768
	v_mfma_f32_32x32x16_bf16 v[0:15], v[68:71], v[76:79], v[0:15]
	ds_read_b128 v[92:95], v107 offset:34816
	s_waitcnt vmcnt(0)
	s_waitcnt lgkmcnt(0)
	s_barrier
	ds_read_b128 v[64:67], v104 offset:49152
	ds_read_b128 v[68:71], v104 offset:51200
	ds_read_b128 v[72:75], v106 offset:49152
	ds_read_b128 v[76:79], v106 offset:51200
	v_mfma_f32_32x32x16_bf16 v[48:63], v[80:83], v[88:91], v[48:63]
	v_mfma_f32_32x32x16_bf16 v[32:47], v[80:83], v[92:95], v[32:47]
	v_mfma_f32_32x32x16_bf16 v[16:31], v[84:87], v[88:91], v[16:31]
	v_mfma_f32_32x32x16_bf16 v[0:15], v[84:87], v[92:95], v[0:15]
	s_waitcnt lgkmcnt(0)
	v_mfma_f32_32x32x16_bf16 v[48:63], v[64:67], v[72:75], v[48:63]
	ds_read_b128 v[80:83], v105 offset:49152
	v_mfma_f32_32x32x16_bf16 v[32:47], v[64:67], v[76:79], v[32:47]
	ds_read_b128 v[84:87], v105 offset:51200
	v_mfma_f32_32x32x16_bf16 v[16:31], v[68:71], v[72:75], v[16:31]
	ds_read_b128 v[88:91], v107 offset:49152
	v_mfma_f32_32x32x16_bf16 v[0:15], v[68:71], v[76:79], v[0:15]
	ds_read_b128 v[92:95], v107 offset:51200
	s_waitcnt lgkmcnt(0)
	v_mfma_f32_32x32x16_bf16 v[48:63], v[80:83], v[88:91], v[48:63]
	v_mfma_f32_32x32x16_bf16 v[32:47], v[80:83], v[92:95], v[32:47]
	v_mfma_f32_32x32x16_bf16 v[16:31], v[84:87], v[88:91], v[16:31]
	v_mfma_f32_32x32x16_bf16 v[0:15], v[84:87], v[92:95], v[0:15]
	s_nop 15
	s_barrier
	s_branch .LBB0_805
.LBB0_814:
	s_or_b64 exec, exec, s[0:1]
	s_movk_i32 s3, 0x200
	s_waitcnt vmcnt(63) expcnt(7) lgkmcnt(15)
	s_barrier
	s_cmp_ge_i32 s2, s3
	s_cbranch_scc0 .LBB0_816
	s_branch .LBB0_867

; template <bool BNN, class AL, class BL>
; __device__ __forceinline__ void gemm_tile(const AL& al, const BL& bl, int K, u16* smem, f32x16 (&acc)[2][2]) {
;     ...
;   G_LOAD(ra0, rb0, 0)
;   G_STORE(ra0, rb0, 0)
;   if (nkt > 1) G_LOAD(ra1, rb1, 1)
;   __syncthreads();
; __device__ __forceinline__ void gemm_nt_phase(const u16* A, int lda, const u16* Bt, int ldb, u16* C, int ldc,
;                               int Mt, int Nt, int K, int qcols, float qscale, u16* smem,
;                               u16* vtx = nullptr, u16* vtc = nullptr, u16* smv = nullptr) {
;     ...
;     for (int t = VBID; t < nS; t += VGRID) {
;       const int ms = t / NtS, ns = t - ms * NtS;
;       const u16* Ab = A + (long)(N_X + ms * 128) * lda;
;       const u16* Bb = Bt + (long)ns * 128 * ldb;
;       auto al = [=](int r, int k) { return ldg16(Ab + (unsigned)(r * lda + k)); };
;       auto bl = [=](int r, int k) { return ldg16(Bb + (unsigned)(r * ldb + k)); };
;       f32x16 acc[2][2];
;       gemm_tile<false>(al, bl, K, smv, acc);
.LBB0_1134:
	s_waitcnt vmcnt(0)
	s_barrier
	v_readfirstlane_b32 s98, v153
	v_bfe_u32 v108, v152, 6, 2
	v_readlane_b32 s100, v252, 0
	v_readlane_b32 s101, v252, 1
	v_readfirstlane_b32 s99, v108
	s_nop 3
	s_sub_u32 s100, s100, 0x170
	s_subb_u32 s101, s101, 0
	s_lshl_b32 vcc_lo, s2, 1
	s_add_u32 vcc_lo, vcc_lo, s98
	s_lshr_b32 vcc_hi, vcc_lo, 3
	s_and_b32 vcc_lo, vcc_lo, 7
	v_mul_u32_u24_e32 v108, 0x12000, v153
	v_add_u32_e32 v108, 16, v108
	v_and_b32_e32 v109, 31, v152
	v_bfe_u32 v110, v152, 2, 2
	v_bfe_u32 v111, v152, 5, 1
	v_xor_b32_e32 v112, v111, v110
	v_lshlrev_b32_e32 v112, 4, v112
	v_xor_b32_e32 v113, 32, v112
	v_bfe_u32 v114, v152, 7, 1
	v_lshl_add_u32 v114, v114, 6, v109
	v_lshl_add_u32 v114, v114, 6, v108
	v_bfe_u32 v115, v152, 6, 1
	v_lshl_add_u32 v115, v115, 6, v109
	v_lshl_add_u32 v115, v115, 6, v108
	v_add_u32_e32 v104, v114, v112
	v_add_u32_e32 v105, v114, v113
	v_add_u32_e32 v115, 0x2000, v115
	v_add_u32_e32 v106, v115, v112
	v_add_u32_e32 v107, v115, v113
	v_bfe_u32 v109, v152, 2, 4
	v_bfe_u32 v110, v152, 4, 2
	v_and_b32_e32 v111, 3, v152
	v_xor_b32_e32 v110, v111, v110
	v_bfe_u32 v111, v152, 6, 2
	v_lshl_add_u32 v109, v111, 5, v109
	s_mov_b32 m0, 0x1600
	v_mul_lo_u32 v112, v109, m0
	v_lshl_add_u32 v112, v110, 4, v112
	s_lshl_b32 s98, s98, 0
	s_mov_b32 s99, s99
	s_lshl_b32 vcc_hi, vcc_hi, 8
	s_or_b32 s98, s98, vcc_hi
	s_lshl_b32 vcc_lo, vcc_lo, 16
	s_or_b32 s98, s98, vcc_lo
	s_load_dwordx2 s[100:101], s[100:101], 0x148
	s_bfe_u32 m0, s98, 0x80008
	s_lshl_b32 m0, m0, 7
	s_add_u32 m0, m0, 0x8000
	s_mul_i32 m0, m0, 0x1600
	s_waitcnt lgkmcnt(0)
	s_add_u32 s100, s100, m0
	s_addc_u32 s101, s101, 0
	v_mov_b32_e32 v113, s101
	v_add_co_u32_e32 v96, vcc, s100, v112
	s_nop 1
	v_addc_co_u32_e32 v97, vcc, 0, v113, vcc
	v_add_co_u32_e32 v98, vcc, 0x16000, v96
	s_nop 1
	v_addc_co_u32_e32 v99, vcc, 0, v97, vcc
	v_readlane_b32 s100, v252, 0
	v_readlane_b32 s101, v252, 1
	s_nop 3
	s_sub_u32 s100, s100, 0x170
	s_subb_u32 s101, s101, 0
	s_load_dwordx2 s[100:101], s[100:101], 0xf8
	s_bfe_u32 m0, s98, 0x80010
	s_lshl_b32 m0, m0, 7
	s_mul_i32 m0, m0, 0x1600
	s_waitcnt lgkmcnt(0)
	s_add_u32 s100, s100, m0
	s_addc_u32 s101, s101, 0
	v_mov_b32_e32 v113, s101
	v_add_co_u32_e32 v100, vcc, s100, v112
	s_nop 1
	v_addc_co_u32_e32 v101, vcc, 0, v113, vcc
	v_add_co_u32_e32 v102, vcc, 0x16000, v100
	s_nop 1
	v_addc_co_u32_e32 v103, vcc, 0, v101, vcc
	s_and_b32 m0, s98, 1
	s_mul_i32 m0, m0, 0x12000
	s_lshl_b32 s99, s99, 11
	s_add_u32 s98, m0, s99
	s_add_u32 s98, s98, 16
	s_add_u32 m0, s98, 0x0
	s_nop 0
	global_load_lds_dwordx4 v[96:97], off
	s_add_u32 m0, s98, 0x400
	s_nop 0
	global_load_lds_dwordx4 v[98:99], off
	s_add_u32 m0, s98, 0x2000
	s_nop 0
	global_load_lds_dwordx4 v[100:101], off
	s_add_u32 m0, s98, 0x2400
	s_nop 0
	global_load_lds_dwordx4 v[102:103], off
	v_lshl_add_u64 v[96:97], v[96:97], 0, 64
	v_lshl_add_u64 v[98:99], v[98:99], 0, 64
	v_lshl_add_u64 v[100:101], v[100:101], 0, 64
	v_lshl_add_u64 v[102:103], v[102:103], 0, 64
	s_add_u32 m0, s98, 0x4000
	s_nop 0
	global_load_lds_dwordx4 v[96:97], off
	s_add_u32 m0, s98, 0x4400
	s_nop 0
	global_load_lds_dwordx4 v[98:99], off
	s_add_u32 m0, s98, 0x6000
	s_nop 0
	global_load_lds_dwordx4 v[100:101], off
	s_add_u32 m0, s98, 0x6400
	s_nop 0
	global_load_lds_dwordx4 v[102:103], off
	v_lshl_add_u64 v[96:97], v[96:97], 0, 64
	v_lshl_add_u64 v[98:99], v[98:99], 0, 64
	v_lshl_add_u64 v[100:101], v[100:101], 0, 64
	v_lshl_add_u64 v[102:103], v[102:103], 0, 64
	s_add_u32 m0, s98, 0x8000
	s_nop 0
	global_load_lds_dwordx4 v[96:97], off
	s_add_u32 m0, s98, 0x8400
	s_nop 0
	global_load_lds_dwordx4 v[98:99], off
	s_add_u32 m0, s98, 0xa000
	s_nop 0
	global_load_lds_dwordx4 v[100:101], off
	s_add_u32 m0, s98, 0xa400
	s_nop 0
	global_load_lds_dwordx4 v[102:103], off
	v_lshl_add_u64 v[96:97], v[96:97], 0, 64
	v_lshl_add_u64 v[98:99], v[98:99], 0, 64
	v_lshl_add_u64 v[100:101], v[100:101], 0, 64
	v_lshl_add_u64 v[102:103], v[102:103], 0, 64
	s_waitcnt vmcnt(8)
	s_barrier
	ds_read_b128 v[64:67], v104 offset:0
	ds_read_b128 v[68:71], v104 offset:2048
	ds_read_b128 v[72:75], v106 offset:0
	ds_read_b128 v[76:79], v106 offset:2048
	s_add_u32 m0, s98, 0xc000
	s_nop 0
	global_load_lds_dwordx4 v[96:97], off
	s_add_u32 m0, s98, 0xc400
	s_nop 0
	global_load_lds_dwordx4 v[98:99], off
	s_add_u32 m0, s98, 0xe000
	s_nop 0
	global_load_lds_dwordx4 v[100:101], off
	s_add_u32 m0, s98, 0xe400
	s_nop 0
	global_load_lds_dwordx4 v[102:103], off
	v_lshl_add_u64 v[96:97], v[96:97], 0, 64
	v_lshl_add_u64 v[98:99], v[98:99], 0, 64
	v_lshl_add_u64 v[100:101], v[100:101], 0, 64
	v_lshl_add_u64 v[102:103], v[102:103], 0, 64
	s_waitcnt lgkmcnt(0)
	v_mfma_f32_32x32x16_bf16 v[48:63], v[64:67], v[72:75], v[48:63]
	ds_read_b128 v[80:83], v105 offset:0
	v_mfma_f32_32x32x16_bf16 v[32:47], v[64:67], v[76:79], v[32:47]
	ds_read_b128 v[84:87], v105 offset:2048
	v_mfma_f32_32x32x16_bf16 v[16:31], v[68:71], v[72:75], v[16:31]
	ds_read_b128 v[88:91], v107 offset:0
	v_mfma_f32_32x32x16_bf16 v[0:15], v[68:71], v[76:79], v[0:15]
	ds_read_b128 v[92:95], v107 offset:2048
	s_waitcnt vmcnt(8)
	s_waitcnt lgkmcnt(0)
	s_barrier
; template <bool BNN, class AL, class BL>
; __device__ __forceinline__ void gemm_tile(const AL& al, const BL& bl, int K, u16* smem, f32x16 (&acc)[2][2]) {
;     ...
;   for (int kt = 0; kt < nkt; kt += 2) {
;     if (kt + 2 < nkt) G_LOAD(ra0, rb0, kt + 2)
;     G_COMPUTE(0)
;     if (kt + 1 < nkt) G_STORE(ra1, rb1, 1)
;     __syncthreads();
;     if (kt + 1 >= nkt) break;
;     if (kt + 3 < nkt) G_LOAD(ra1, rb1, kt + 3)
;     G_COMPUTE(1)
;     if (kt + 2 < nkt) G_STORE(ra0, rb0, 0)
;     __syncthreads();
;   }
	ds_read_b128 v[64:67], v104 offset:16384
	ds_read_b128 v[68:71], v104 offset:18432
	ds_read_b128 v[72:75], v106 offset:16384
	ds_read_b128 v[76:79], v106 offset:18432
	s_add_u32 m0, s98, 0x0
	v_mfma_f32_32x32x16_bf16 v[48:63], v[80:83], v[88:91], v[48:63]
	global_load_lds_dwordx4 v[96:97], off
	s_add_u32 m0, s98, 0x400
	v_mfma_f32_32x32x16_bf16 v[32:47], v[80:83], v[92:95], v[32:47]
	global_load_lds_dwordx4 v[98:99], off
	s_add_u32 m0, s98, 0x2000
	v_mfma_f32_32x32x16_bf16 v[16:31], v[84:87], v[88:91], v[16:31]
	global_load_lds_dwordx4 v[100:101], off
	s_add_u32 m0, s98, 0x2400
	v_mfma_f32_32x32x16_bf16 v[0:15], v[84:87], v[92:95], v[0:15]
	global_load_lds_dwordx4 v[102:103], off
	v_lshl_add_u64 v[96:97], v[96:97], 0, 64
	v_lshl_add_u64 v[98:99], v[98:99], 0, 64
	v_lshl_add_u64 v[100:101], v[100:101], 0, 64
	v_lshl_add_u64 v[102:103], v[102:103], 0, 64
	s_waitcnt lgkmcnt(0)
	v_mfma_f32_32x32x16_bf16 v[48:63], v[64:67], v[72:75], v[48:63]
	ds_read_b128 v[80:83], v105 offset:16384
	v_mfma_f32_32x32x16_bf16 v[32:47], v[64:67], v[76:79], v[32:47]
	ds_read_b128 v[84:87], v105 offset:18432
	v_mfma_f32_32x32x16_bf16 v[16:31], v[68:71], v[72:75], v[16:31]
	ds_read_b128 v[88:91], v107 offset:16384
	v_mfma_f32_32x32x16_bf16 v[0:15], v[68:71], v[76:79], v[0:15]
	ds_read_b128 v[92:95], v107 offset:18432
	s_waitcnt vmcnt(8)
	s_waitcnt lgkmcnt(0)
	s_barrier
	ds_read_b128 v[64:67], v104 offset:32768
	ds_read_b128 v[68:71], v104 offset:34816
	ds_read_b128 v[72:75], v106 offset:32768
	ds_read_b128 v[76:79], v106 offset:34816
	s_add_u32 m0, s98, 0x4000
	v_mfma_f32_32x32x16_bf16 v[48:63], v[80:83], v[88:91], v[48:63]
	global_load_lds_dwordx4 v[96:97], off
	s_add_u32 m0, s98, 0x4400
	v_mfma_f32_32x32x16_bf16 v[32:47], v[80:83], v[92:95], v[32:47]
	global_load_lds_dwordx4 v[98:99], off
	s_add_u32 m0, s98, 0x6000
	v_mfma_f32_32x32x16_bf16 v[16:31], v[84:87], v[88:91], v[16:31]
	global_load_lds_dwordx4 v[100:101], off
	s_add_u32 m0, s98, 0x6400
	v_mfma_f32_32x32x16_bf16 v[0:15], v[84:87], v[92:95], v[0:15]
	global_load_lds_dwordx4 v[102:103], off
	v_lshl_add_u64 v[96:97], v[96:97], 0, 64
	v_lshl_add_u64 v[98:99], v[98:99], 0, 64
	v_lshl_add_u64 v[100:101], v[100:101], 0, 64
	v_lshl_add_u64 v[102:103], v[102:103], 0, 64
	s_waitcnt lgkmcnt(0)
	v_mfma_f32_32x32x16_bf16 v[48:63], v[64:67], v[72:75], v[48:63]
	ds_read_b128 v[80:83], v105 offset:32768
	v_mfma_f32_32x32x16_bf16 v[32:47], v[64:67], v[76:79], v[32:47]
	ds_read_b128 v[84:87], v105 offset:34816
	v_mfma_f32_32x32x16_bf16 v[16:31], v[68:71], v[72:75], v[16:31]
	ds_read_b128 v[88:91], v107 offset:32768
	v_mfma_f32_32x32x16_bf16 v[0:15], v[68:71], v[76:79], v[0:15]
	ds_read_b128 v[92:95], v107 offset:34816
	s_waitcnt vmcnt(8)
	s_waitcnt lgkmcnt(0)
	s_barrier
	ds_read_b128 v[64:67], v104 offset:49152
	ds_read_b128 v[68:71], v104 offset:51200
	ds_read_b128 v[72:75], v106 offset:49152
	ds_read_b128 v[76:79], v106 offset:51200
	s_add_u32 m0, s98, 0x8000
	v_mfma_f32_32x32x16_bf16 v[48:63], v[80:83], v[88:91], v[48:63]
	global_load_lds_dwordx4 v[96:97], off
	s_add_u32 m0, s98, 0x8400
	v_mfma_f32_32x32x16_bf16 v[32:47], v[80:83], v[92:95], v[32:47]
	global_load_lds_dwordx4 v[98:99], off
	s_add_u32 m0, s98, 0xa000
	v_mfma_f32_32x32x16_bf16 v[16:31], v[84:87], v[88:91], v[16:31]
	global_load_lds_dwordx4 v[100:101], off
	s_add_u32 m0, s98, 0xa400
	v_mfma_f32_32x32x16_bf16 v[0:15], v[84:87], v[92:95], v[0:15]
	global_load_lds_dwordx4 v[102:103], off
	v_lshl_add_u64 v[96:97], v[96:97], 0, 64
	v_lshl_add_u64 v[98:99], v[98:99], 0, 64
	v_lshl_add_u64 v[100:101], v[100:101], 0, 64
	v_lshl_add_u64 v[102:103], v[102:103], 0, 64
	s_waitcnt lgkmcnt(0)
	v_mfma_f32_32x32x16_bf16 v[48:63], v[64:67], v[72:75], v[48:63]
	ds_read_b128 v[80:83], v105 offset:49152
	v_mfma_f32_32x32x16_bf16 v[32:47], v[64:67], v[76:79], v[32:47]
	ds_read_b128 v[84:87], v105 offset:51200
	v_mfma_f32_32x32x16_bf16 v[16:31], v[68:71], v[72:75], v[16:31]
	ds_read_b128 v[88:91], v107 offset:49152
	v_mfma_f32_32x32x16_bf16 v[0:15], v[68:71], v[76:79], v[0:15]
	ds_read_b128 v[92:95], v107 offset:51200
	s_waitcnt vmcnt(8)
	s_waitcnt lgkmcnt(0)
	s_mov_b32 s99, 20
.Lmy_pre_p3_loop:
	s_barrier
	ds_read_b128 v[64:67], v104 offset:0
	ds_read_b128 v[68:71], v104 offset:2048
	ds_read_b128 v[72:75], v106 offset:0
	ds_read_b128 v[76:79], v106 offset:2048
	s_add_u32 m0, s98, 0xc000
	v_mfma_f32_32x32x16_bf16 v[48:63], v[80:83], v[88:91], v[48:63]
	global_load_lds_dwordx4 v[96:97], off
	s_add_u32 m0, s98, 0xc400
	v_mfma_f32_32x32x16_bf16 v[32:47], v[80:83], v[92:95], v[32:47]
	global_load_lds_dwordx4 v[98:99], off
	s_add_u32 m0, s98, 0xe000
	v_mfma_f32_32x32x16_bf16 v[16:31], v[84:87], v[88:91], v[16:31]
	global_load_lds_dwordx4 v[100:101], off
	s_add_u32 m0, s98, 0xe400
	v_mfma_f32_32x32x16_bf16 v[0:15], v[84:87], v[92:95], v[0:15]
	global_load_lds_dwordx4 v[102:103], off
	v_lshl_add_u64 v[96:97], v[96:97], 0, 64
	v_lshl_add_u64 v[98:99], v[98:99], 0, 64
	v_lshl_add_u64 v[100:101], v[100:101], 0, 64
	v_lshl_add_u64 v[102:103], v[102:103], 0, 64
	s_waitcnt lgkmcnt(0)
	v_mfma_f32_32x32x16_bf16 v[48:63], v[64:67], v[72:75], v[48:63]
	ds_read_b128 v[80:83], v105 offset:0
	v_mfma_f32_32x32x16_bf16 v[32:47], v[64:67], v[76:79], v[32:47]
	ds_read_b128 v[84:87], v105 offset:2048
	v_mfma_f32_32x32x16_bf16 v[16:31], v[68:71], v[72:75], v[16:31]
	ds_read_b128 v[88:91], v107 offset:0
	v_mfma_f32_32x32x16_bf16 v[0:15], v[68:71], v[76:79], v[0:15]
	ds_read_b128 v[92:95], v107 offset:2048
	s_waitcnt vmcnt(8)
	s_waitcnt lgkmcnt(0)
	s_barrier
; template <bool BNN, class AL, class BL>
; __device__ __forceinline__ void gemm_tile(const AL& al, const BL& bl, int K, u16* smem, f32x16 (&acc)[2][2]) {
;     ...
;   for (int kt = 0; kt < nkt; kt += 2) {
;     if (kt + 2 < nkt) G_LOAD(ra0, rb0, kt + 2)
;     G_COMPUTE(0)
;     if (kt + 1 < nkt) G_STORE(ra1, rb1, 1)
;     __syncthreads();
;     if (kt + 1 >= nkt) break;
;     if (kt + 3 < nkt) G_LOAD(ra1, rb1, kt + 3)
;     G_COMPUTE(1)
;     if (kt + 2 < nkt) G_STORE(ra0, rb0, 0)
;     __syncthreads();
;   }
	ds_read_b128 v[64:67], v104 offset:16384
	ds_read_b128 v[68:71], v104 offset:18432
	ds_read_b128 v[72:75], v106 offset:16384
	ds_read_b128 v[76:79], v106 offset:18432
	s_add_u32 m0, s98, 0x0
	v_mfma_f32_32x32x16_bf16 v[48:63], v[80:83], v[88:91], v[48:63]
	global_load_lds_dwordx4 v[96:97], off
	s_add_u32 m0, s98, 0x400
	v_mfma_f32_32x32x16_bf16 v[32:47], v[80:83], v[92:95], v[32:47]
	global_load_lds_dwordx4 v[98:99], off
	s_add_u32 m0, s98, 0x2000
	v_mfma_f32_32x32x16_bf16 v[16:31], v[84:87], v[88:91], v[16:31]
	global_load_lds_dwordx4 v[100:101], off
	s_add_u32 m0, s98, 0x2400
	v_mfma_f32_32x32x16_bf16 v[0:15], v[84:87], v[92:95], v[0:15]
	global_load_lds_dwordx4 v[102:103], off
	v_lshl_add_u64 v[96:97], v[96:97], 0, 64
	v_lshl_add_u64 v[98:99], v[98:99], 0, 64
	v_lshl_add_u64 v[100:101], v[100:101], 0, 64
	v_lshl_add_u64 v[102:103], v[102:103], 0, 64
	s_waitcnt lgkmcnt(0)
	v_mfma_f32_32x32x16_bf16 v[48:63], v[64:67], v[72:75], v[48:63]
	ds_read_b128 v[80:83], v105 offset:16384
	v_mfma_f32_32x32x16_bf16 v[32:47], v[64:67], v[76:79], v[32:47]
	ds_read_b128 v[84:87], v105 offset:18432
	v_mfma_f32_32x32x16_bf16 v[16:31], v[68:71], v[72:75], v[16:31]
	ds_read_b128 v[88:91], v107 offset:16384
	v_mfma_f32_32x32x16_bf16 v[0:15], v[68:71], v[76:79], v[0:15]
	ds_read_b128 v[92:95], v107 offset:18432
	s_waitcnt vmcnt(8)
	s_waitcnt lgkmcnt(0)
	s_barrier
	ds_read_b128 v[64:67], v104 offset:32768
	ds_read_b128 v[68:71], v104 offset:34816
	ds_read_b128 v[72:75], v106 offset:32768
	ds_read_b128 v[76:79], v106 offset:34816
	s_add_u32 m0, s98, 0x4000
	v_mfma_f32_32x32x16_bf16 v[48:63], v[80:83], v[88:91], v[48:63]
	global_load_lds_dwordx4 v[96:97], off
	s_add_u32 m0, s98, 0x4400
	v_mfma_f32_32x32x16_bf16 v[32:47], v[80:83], v[92:95], v[32:47]
	global_load_lds_dwordx4 v[98:99], off
	s_add_u32 m0, s98, 0x6000
	v_mfma_f32_32x32x16_bf16 v[16:31], v[84:87], v[88:91], v[16:31]
	global_load_lds_dwordx4 v[100:101], off
	s_add_u32 m0, s98, 0x6400
	v_mfma_f32_32x32x16_bf16 v[0:15], v[84:87], v[92:95], v[0:15]
	global_load_lds_dwordx4 v[102:103], off
	v_lshl_add_u64 v[96:97], v[96:97], 0, 64
	v_lshl_add_u64 v[98:99], v[98:99], 0, 64
	v_lshl_add_u64 v[100:101], v[100:101], 0, 64
	v_lshl_add_u64 v[102:103], v[102:103], 0, 64
	s_waitcnt lgkmcnt(0)
	v_mfma_f32_32x32x16_bf16 v[48:63], v[64:67], v[72:75], v[48:63]
	ds_read_b128 v[80:83], v105 offset:32768
	v_mfma_f32_32x32x16_bf16 v[32:47], v[64:67], v[76:79], v[32:47]
	ds_read_b128 v[84:87], v105 offset:34816
	v_mfma_f32_32x32x16_bf16 v[16:31], v[68:71], v[72:75], v[16:31]
	ds_read_b128 v[88:91], v107 offset:32768
	v_mfma_f32_32x32x16_bf16 v[0:15], v[68:71], v[76:79], v[0:15]
	ds_read_b128 v[92:95], v107 offset:34816
	s_waitcnt vmcnt(8)
	s_waitcnt lgkmcnt(0)
	s_barrier
	ds_read_b128 v[64:67], v104 offset:49152
	ds_read_b128 v[68:71], v104 offset:51200
	ds_read_b128 v[72:75], v106 offset:49152
	ds_read_b128 v[76:79], v106 offset:51200
	s_add_u32 m0, s98, 0x8000
	v_mfma_f32_32x32x16_bf16 v[48:63], v[80:83], v[88:91], v[48:63]
	global_load_lds_dwordx4 v[96:97], off
	s_add_u32 m0, s98, 0x8400
	v_mfma_f32_32x32x16_bf16 v[32:47], v[80:83], v[92:95], v[32:47]
	global_load_lds_dwordx4 v[98:99], off
	s_add_u32 m0, s98, 0xa000
	v_mfma_f32_32x32x16_bf16 v[16:31], v[84:87], v[88:91], v[16:31]
	global_load_lds_dwordx4 v[100:101], off
	s_add_u32 m0, s98, 0xa400
	v_mfma_f32_32x32x16_bf16 v[0:15], v[84:87], v[92:95], v[0:15]
	global_load_lds_dwordx4 v[102:103], off
	v_lshl_add_u64 v[96:97], v[96:97], 0, 64
	v_lshl_add_u64 v[98:99], v[98:99], 0, 64
	v_lshl_add_u64 v[100:101], v[100:101], 0, 64
	v_lshl_add_u64 v[102:103], v[102:103], 0, 64
	s_waitcnt lgkmcnt(0)
	v_mfma_f32_32x32x16_bf16 v[48:63], v[64:67], v[72:75], v[48:63]
	ds_read_b128 v[80:83], v105 offset:49152
	v_mfma_f32_32x32x16_bf16 v[32:47], v[64:67], v[76:79], v[32:47]
	ds_read_b128 v[84:87], v105 offset:51200
	v_mfma_f32_32x32x16_bf16 v[16:31], v[68:71], v[72:75], v[16:31]
	ds_read_b128 v[88:91], v107 offset:49152
	v_mfma_f32_32x32x16_bf16 v[0:15], v[68:71], v[76:79], v[0:15]
	ds_read_b128 v[92:95], v107 offset:51200
	s_waitcnt vmcnt(8)
	s_waitcnt lgkmcnt(0)
	s_sub_u32 s99, s99, 1
	s_cmp_lg_u32 s99, 0
	s_cbranch_scc1 .Lmy_pre_p3_loop
	s_barrier
; template <bool BNN, class AL, class BL>
; __device__ __forceinline__ void gemm_tile(const AL& al, const BL& bl, int K, u16* smem, f32x16 (&acc)[2][2]) {
;     ...
;   for (int kt = 0; kt < nkt; kt += 2) {
;     if (kt + 2 < nkt) G_LOAD(ra0, rb0, kt + 2)
;     G_COMPUTE(0)
;     if (kt + 1 < nkt) G_STORE(ra1, rb1, 1)
;     __syncthreads();
;     if (kt + 1 >= nkt) break;
;     if (kt + 3 < nkt) G_LOAD(ra1, rb1, kt + 3)
;     G_COMPUTE(1)
;     if (kt + 2 < nkt) G_STORE(ra0, rb0, 0)
;     __syncthreads();
;   }
; __device__ __forceinline__ void gemm_nt_phase(const u16* A, int lda, const u16* Bt, int ldb, u16* C, int ldc,
;                               int Mt, int Nt, int K, int qcols, float qscale, u16* smem,
;                               u16* vtx = nullptr, u16* vtc = nullptr, u16* smv = nullptr) {
;     ...
;     __syncthreads();
;     Mt = 128;
;   }
;   const int nT = Mt * Nt;
;   for (int t = blockIdx.x; t < nT; t += gridDim.x) {
	ds_read_b128 v[64:67], v104 offset:0
	ds_read_b128 v[68:71], v104 offset:2048
	ds_read_b128 v[72:75], v106 offset:0
	ds_read_b128 v[76:79], v106 offset:2048
	s_add_u32 m0, s98, 0xc000
	v_mfma_f32_32x32x16_bf16 v[48:63], v[80:83], v[88:91], v[48:63]
	global_load_lds_dwordx4 v[96:97], off
	s_add_u32 m0, s98, 0xc400
	v_mfma_f32_32x32x16_bf16 v[32:47], v[80:83], v[92:95], v[32:47]
	global_load_lds_dwordx4 v[98:99], off
	s_add_u32 m0, s98, 0xe000
	v_mfma_f32_32x32x16_bf16 v[16:31], v[84:87], v[88:91], v[16:31]
	global_load_lds_dwordx4 v[100:101], off
	s_add_u32 m0, s98, 0xe400
	v_mfma_f32_32x32x16_bf16 v[0:15], v[84:87], v[92:95], v[0:15]
	global_load_lds_dwordx4 v[102:103], off
	v_lshl_add_u64 v[96:97], v[96:97], 0, 64
	v_lshl_add_u64 v[98:99], v[98:99], 0, 64
	v_lshl_add_u64 v[100:101], v[100:101], 0, 64
	v_lshl_add_u64 v[102:103], v[102:103], 0, 64
	s_waitcnt lgkmcnt(0)
	v_mfma_f32_32x32x16_bf16 v[48:63], v[64:67], v[72:75], v[48:63]
	ds_read_b128 v[80:83], v105 offset:0
	v_mfma_f32_32x32x16_bf16 v[32:47], v[64:67], v[76:79], v[32:47]
	ds_read_b128 v[84:87], v105 offset:2048
	v_mfma_f32_32x32x16_bf16 v[16:31], v[68:71], v[72:75], v[16:31]
	ds_read_b128 v[88:91], v107 offset:0
	v_mfma_f32_32x32x16_bf16 v[0:15], v[68:71], v[76:79], v[0:15]
	ds_read_b128 v[92:95], v107 offset:2048
	s_waitcnt vmcnt(8)
	s_waitcnt lgkmcnt(0)
	s_barrier
	ds_read_b128 v[64:67], v104 offset:16384
	ds_read_b128 v[68:71], v104 offset:18432
	ds_read_b128 v[72:75], v106 offset:16384
	ds_read_b128 v[76:79], v106 offset:18432
	v_mfma_f32_32x32x16_bf16 v[48:63], v[80:83], v[88:91], v[48:63]
	v_mfma_f32_32x32x16_bf16 v[32:47], v[80:83], v[92:95], v[32:47]
	v_mfma_f32_32x32x16_bf16 v[16:31], v[84:87], v[88:91], v[16:31]
	v_mfma_f32_32x32x16_bf16 v[0:15], v[84:87], v[92:95], v[0:15]
	s_waitcnt lgkmcnt(0)
	v_mfma_f32_32x32x16_bf16 v[48:63], v[64:67], v[72:75], v[48:63]
	ds_read_b128 v[80:83], v105 offset:16384
	v_mfma_f32_32x32x16_bf16 v[32:47], v[64:67], v[76:79], v[32:47]
	ds_read_b128 v[84:87], v105 offset:18432
	v_mfma_f32_32x32x16_bf16 v[16:31], v[68:71], v[72:75], v[16:31]
	ds_read_b128 v[88:91], v107 offset:16384
	v_mfma_f32_32x32x16_bf16 v[0:15], v[68:71], v[76:79], v[0:15]
	ds_read_b128 v[92:95], v107 offset:18432
	s_waitcnt vmcnt(4)
	s_waitcnt lgkmcnt(0)
	s_barrier
	ds_read_b128 v[64:67], v104 offset:32768
	ds_read_b128 v[68:71], v104 offset:34816
	ds_read_b128 v[72:75], v106 offset:32768
	ds_read_b128 v[76:79], v106 offset:34816
	v_mfma_f32_32x32x16_bf16 v[48:63], v[80:83], v[88:91], v[48:63]
	v_mfma_f32_32x32x16_bf16 v[32:47], v[80:83], v[92:95], v[32:47]
	v_mfma_f32_32x32x16_bf16 v[16:31], v[84:87], v[88:91], v[16:31]
	v_mfma_f32_32x32x16_bf16 v[0:15], v[84:87], v[92:95], v[0:15]
	s_waitcnt lgkmcnt(0)
	v_mfma_f32_32x32x16_bf16 v[48:63], v[64:67], v[72:75], v[48:63]
	ds_read_b128 v[80:83], v105 offset:32768
	v_mfma_f32_32x32x16_bf16 v[32:47], v[64:67], v[76:79], v[32:47]
	ds_read_b128 v[84:87], v105 offset:34816
	v_mfma_f32_32x32x16_bf16 v[16:31], v[68:71], v[72:75], v[16:31]
	ds_read_b128 v[88:91], v107 offset:32768
	v_mfma_f32_32x32x16_bf16 v[0:15], v[68:71], v[76:79], v[0:15]
	ds_read_b128 v[92:95], v107 offset:34816
	s_waitcnt vmcnt(0)
	s_waitcnt lgkmcnt(0)
	s_barrier
	ds_read_b128 v[64:67], v104 offset:49152
	ds_read_b128 v[68:71], v104 offset:51200
	ds_read_b128 v[72:75], v106 offset:49152
	ds_read_b128 v[76:79], v106 offset:51200
	v_mfma_f32_32x32x16_bf16 v[48:63], v[80:83], v[88:91], v[48:63]
	v_mfma_f32_32x32x16_bf16 v[32:47], v[80:83], v[92:95], v[32:47]
	v_mfma_f32_32x32x16_bf16 v[16:31], v[84:87], v[88:91], v[16:31]
	v_mfma_f32_32x32x16_bf16 v[0:15], v[84:87], v[92:95], v[0:15]
	s_waitcnt lgkmcnt(0)
	v_mfma_f32_32x32x16_bf16 v[48:63], v[64:67], v[72:75], v[48:63]
	ds_read_b128 v[80:83], v105 offset:49152
	v_mfma_f32_32x32x16_bf16 v[32:47], v[64:67], v[76:79], v[32:47]
	ds_read_b128 v[84:87], v105 offset:51200
	v_mfma_f32_32x32x16_bf16 v[16:31], v[68:71], v[72:75], v[16:31]
	ds_read_b128 v[88:91], v107 offset:49152
	v_mfma_f32_32x32x16_bf16 v[0:15], v[68:71], v[76:79], v[0:15]
	ds_read_b128 v[92:95], v107 offset:51200
	s_waitcnt lgkmcnt(0)
	v_mfma_f32_32x32x16_bf16 v[48:63], v[80:83], v[88:91], v[48:63]
	v_mfma_f32_32x32x16_bf16 v[32:47], v[80:83], v[92:95], v[32:47]
	v_mfma_f32_32x32x16_bf16 v[16:31], v[84:87], v[88:91], v[16:31]
	v_mfma_f32_32x32x16_bf16 v[0:15], v[84:87], v[92:95], v[0:15]
	s_nop 15
	s_barrier
	s_branch .LBB0_1131
.LBB0_1140:
	s_or_b64 exec, exec, s[0:1]
	s_movk_i32 s3, 0x200
	s_waitcnt vmcnt(63) expcnt(7) lgkmcnt(15)
	s_barrier
	s_cmp_ge_i32 s2, s3
	s_cbranch_scc0 .LBB0_1142
	s_branch .LBB0_1193

; template <bool BNN, class AL, class BL>
; __device__ __forceinline__ void gemm_tile(const AL& al, const BL& bl, int K, u16* smem, f32x16 (&acc)[2][2]) {
;     ...
;   G_LOAD(ra0, rb0, 0)
;   G_STORE(ra0, rb0, 0)
;   if (nkt > 1) G_LOAD(ra1, rb1, 1)
;   __syncthreads();
; __device__ __forceinline__ void gemm_nt_phase(const u16* A, int lda, const u16* Bt, int ldb, u16* C, int ldc,
;                               int Mt, int Nt, int K, int qcols, float qscale, u16* smem,
;                               u16* vtx = nullptr, u16* vtc = nullptr, u16* smv = nullptr) {
;     ...
;     for (int t = VBID; t < nS; t += VGRID) {
;       const int ms = t / NtS, ns = t - ms * NtS;
;       const u16* Ab = A + (long)(N_X + ms * 128) * lda;
;       const u16* Bb = Bt + (long)ns * 128 * ldb;
;       auto al = [=](int r, int k) { return ldg16(Ab + (unsigned)(r * lda + k)); };
;       auto bl = [=](int r, int k) { return ldg16(Bb + (unsigned)(r * ldb + k)); };
;       f32x16 acc[2][2];
;       gemm_tile<false>(al, bl, K, smv, acc);
.LBB0_1364:
	s_waitcnt vmcnt(0)
	s_barrier
	v_readfirstlane_b32 s98, v153
	v_bfe_u32 v108, v152, 6, 2
	v_readlane_b32 s100, v252, 0
	v_readlane_b32 s101, v252, 1
	v_readfirstlane_b32 s99, v108
	s_nop 3
	s_sub_u32 s100, s100, 0x170
	s_subb_u32 s101, s101, 0
	s_lshl_b32 vcc_lo, s2, 1
	s_add_u32 vcc_lo, vcc_lo, s98
	s_mul_i32 vcc_hi, vcc_lo, 2731
	s_lshr_b32 vcc_hi, vcc_hi, 16
	s_mul_i32 m0, vcc_hi, 24
	s_sub_u32 vcc_lo, vcc_lo, m0
	v_mul_u32_u24_e32 v108, 0x12000, v153
	v_add_u32_e32 v108, 16, v108
	v_and_b32_e32 v109, 31, v152
	v_bfe_u32 v110, v152, 2, 2
	v_bfe_u32 v111, v152, 5, 1
	v_xor_b32_e32 v112, v111, v110
	v_lshlrev_b32_e32 v112, 4, v112
	v_xor_b32_e32 v113, 32, v112
	v_bfe_u32 v114, v152, 7, 1
	v_lshl_add_u32 v114, v114, 6, v109
	v_lshl_add_u32 v114, v114, 6, v108
	v_bfe_u32 v115, v152, 6, 1
	v_lshl_add_u32 v115, v115, 6, v109
	v_lshl_add_u32 v115, v115, 6, v108
	v_add_u32_e32 v104, v114, v112
	v_add_u32_e32 v105, v114, v113
	v_add_u32_e32 v115, 0x2000, v115
	v_add_u32_e32 v106, v115, v112
	v_add_u32_e32 v107, v115, v113
	v_bfe_u32 v109, v152, 2, 4
	v_bfe_u32 v110, v152, 4, 2
	v_and_b32_e32 v111, 3, v152
	v_xor_b32_e32 v110, v111, v110
	v_bfe_u32 v111, v152, 6, 2
	v_lshl_add_u32 v109, v111, 5, v109
	s_mov_b32 m0, 0x800
	v_mul_lo_u32 v112, v109, m0
	v_lshl_add_u32 v112, v110, 4, v112
	s_lshl_b32 s98, s98, 0
	s_mov_b32 s99, s99
	s_lshl_b32 vcc_hi, vcc_hi, 8
	s_or_b32 s98, s98, vcc_hi
	s_lshl_b32 vcc_lo, vcc_lo, 16
	s_or_b32 s98, s98, vcc_lo
	s_load_dwordx2 s[100:101], s[100:101], 0x140
	s_bfe_u32 m0, s98, 0x80008
	s_lshl_b32 m0, m0, 7
	s_add_u32 m0, m0, 0x8000
	s_mul_i32 m0, m0, 0x800
	s_waitcnt lgkmcnt(0)
	s_add_u32 s100, s100, m0
	s_addc_u32 s101, s101, 0
	v_mov_b32_e32 v113, s101
	v_add_co_u32_e32 v96, vcc, s100, v112
	s_nop 1
	v_addc_co_u32_e32 v97, vcc, 0, v113, vcc
	v_add_co_u32_e32 v98, vcc, 0x8000, v96
	s_nop 1
	v_addc_co_u32_e32 v99, vcc, 0, v97, vcc
	v_readlane_b32 s100, v252, 0
	v_readlane_b32 s101, v252, 1
	s_nop 3
	s_sub_u32 s100, s100, 0x170
	s_subb_u32 s101, s101, 0
	s_load_dwordx2 s[100:101], s[100:101], 0xe0
	s_bfe_u32 m0, s98, 0x80010
	s_lshl_b32 m0, m0, 7
	s_mul_i32 m0, m0, 0x800
	s_waitcnt lgkmcnt(0)
	s_add_u32 s100, s100, m0
	s_addc_u32 s101, s101, 0
	v_mov_b32_e32 v113, s101
	v_add_co_u32_e32 v100, vcc, s100, v112
	s_nop 1
	v_addc_co_u32_e32 v101, vcc, 0, v113, vcc
	v_add_co_u32_e32 v102, vcc, 0x8000, v100
	s_nop 1
	v_addc_co_u32_e32 v103, vcc, 0, v101, vcc
	s_and_b32 m0, s98, 1
	s_mul_i32 m0, m0, 0x12000
	s_lshl_b32 s99, s99, 11
	s_add_u32 s98, m0, s99
	s_add_u32 s98, s98, 16
	s_add_u32 m0, s98, 0x0
	s_nop 0
	global_load_lds_dwordx4 v[96:97], off
	s_add_u32 m0, s98, 0x400
	s_nop 0
	global_load_lds_dwordx4 v[98:99], off
	s_add_u32 m0, s98, 0x2000
	s_nop 0
	global_load_lds_dwordx4 v[100:101], off
	s_add_u32 m0, s98, 0x2400
	s_nop 0
	global_load_lds_dwordx4 v[102:103], off
	v_lshl_add_u64 v[96:97], v[96:97], 0, 64
	v_lshl_add_u64 v[98:99], v[98:99], 0, 64
	v_lshl_add_u64 v[100:101], v[100:101], 0, 64
	v_lshl_add_u64 v[102:103], v[102:103], 0, 64
	s_add_u32 m0, s98, 0x4000
	s_nop 0
	global_load_lds_dwordx4 v[96:97], off
	s_add_u32 m0, s98, 0x4400
	s_nop 0
	global_load_lds_dwordx4 v[98:99], off
	s_add_u32 m0, s98, 0x6000
	s_nop 0
	global_load_lds_dwordx4 v[100:101], off
	s_add_u32 m0, s98, 0x6400
	s_nop 0
	global_load_lds_dwordx4 v[102:103], off
	v_lshl_add_u64 v[96:97], v[96:97], 0, 64
	v_lshl_add_u64 v[98:99], v[98:99], 0, 64
	v_lshl_add_u64 v[100:101], v[100:101], 0, 64
	v_lshl_add_u64 v[102:103], v[102:103], 0, 64
	s_add_u32 m0, s98, 0x8000
	s_nop 0
	global_load_lds_dwordx4 v[96:97], off
	s_add_u32 m0, s98, 0x8400
	s_nop 0
	global_load_lds_dwordx4 v[98:99], off
	s_add_u32 m0, s98, 0xa000
	s_nop 0
	global_load_lds_dwordx4 v[100:101], off
	s_add_u32 m0, s98, 0xa400
	s_nop 0
	global_load_lds_dwordx4 v[102:103], off
	v_lshl_add_u64 v[96:97], v[96:97], 0, 64
	v_lshl_add_u64 v[98:99], v[98:99], 0, 64
	v_lshl_add_u64 v[100:101], v[100:101], 0, 64
	v_lshl_add_u64 v[102:103], v[102:103], 0, 64
	s_waitcnt vmcnt(8)
	s_barrier
	ds_read_b128 v[64:67], v104 offset:0
	ds_read_b128 v[68:71], v104 offset:2048
	ds_read_b128 v[72:75], v106 offset:0
	ds_read_b128 v[76:79], v106 offset:2048
	s_add_u32 m0, s98, 0xc000
	s_nop 0
	global_load_lds_dwordx4 v[96:97], off
	s_add_u32 m0, s98, 0xc400
	s_nop 0
	global_load_lds_dwordx4 v[98:99], off
	s_add_u32 m0, s98, 0xe000
	s_nop 0
	global_load_lds_dwordx4 v[100:101], off
	s_add_u32 m0, s98, 0xe400
	s_nop 0
	global_load_lds_dwordx4 v[102:103], off
	v_lshl_add_u64 v[96:97], v[96:97], 0, 64
	v_lshl_add_u64 v[98:99], v[98:99], 0, 64
	v_lshl_add_u64 v[100:101], v[100:101], 0, 64
	v_lshl_add_u64 v[102:103], v[102:103], 0, 64
	s_waitcnt lgkmcnt(0)
	v_mfma_f32_32x32x16_bf16 v[48:63], v[64:67], v[72:75], v[48:63]
	ds_read_b128 v[80:83], v105 offset:0
	v_mfma_f32_32x32x16_bf16 v[32:47], v[64:67], v[76:79], v[32:47]
	ds_read_b128 v[84:87], v105 offset:2048
	v_mfma_f32_32x32x16_bf16 v[16:31], v[68:71], v[72:75], v[16:31]
	ds_read_b128 v[88:91], v107 offset:0
	v_mfma_f32_32x32x16_bf16 v[0:15], v[68:71], v[76:79], v[0:15]
	ds_read_b128 v[92:95], v107 offset:2048
	s_waitcnt vmcnt(8)
	s_waitcnt lgkmcnt(0)
	s_barrier
; template <bool BNN, class AL, class BL>
; __device__ __forceinline__ void gemm_tile(const AL& al, const BL& bl, int K, u16* smem, f32x16 (&acc)[2][2]) {
;     ...
;   for (int kt = 0; kt < nkt; kt += 2) {
;     if (kt + 2 < nkt) G_LOAD(ra0, rb0, kt + 2)
;     G_COMPUTE(0)
;     if (kt + 1 < nkt) G_STORE(ra1, rb1, 1)
;     __syncthreads();
;     if (kt + 1 >= nkt) break;
;     if (kt + 3 < nkt) G_LOAD(ra1, rb1, kt + 3)
;     G_COMPUTE(1)
;     if (kt + 2 < nkt) G_STORE(ra0, rb0, 0)
;     __syncthreads();
;   }
	ds_read_b128 v[64:67], v104 offset:16384
	ds_read_b128 v[68:71], v104 offset:18432
	ds_read_b128 v[72:75], v106 offset:16384
	ds_read_b128 v[76:79], v106 offset:18432
	s_add_u32 m0, s98, 0x0
	v_mfma_f32_32x32x16_bf16 v[48:63], v[80:83], v[88:91], v[48:63]
	global_load_lds_dwordx4 v[96:97], off
	s_add_u32 m0, s98, 0x400
	v_mfma_f32_32x32x16_bf16 v[32:47], v[80:83], v[92:95], v[32:47]
	global_load_lds_dwordx4 v[98:99], off
	s_add_u32 m0, s98, 0x2000
	v_mfma_f32_32x32x16_bf16 v[16:31], v[84:87], v[88:91], v[16:31]
	global_load_lds_dwordx4 v[100:101], off
	s_add_u32 m0, s98, 0x2400
	v_mfma_f32_32x32x16_bf16 v[0:15], v[84:87], v[92:95], v[0:15]
	global_load_lds_dwordx4 v[102:103], off
	v_lshl_add_u64 v[96:97], v[96:97], 0, 64
	v_lshl_add_u64 v[98:99], v[98:99], 0, 64
	v_lshl_add_u64 v[100:101], v[100:101], 0, 64
	v_lshl_add_u64 v[102:103], v[102:103], 0, 64
	s_waitcnt lgkmcnt(0)
	v_mfma_f32_32x32x16_bf16 v[48:63], v[64:67], v[72:75], v[48:63]
	ds_read_b128 v[80:83], v105 offset:16384
	v_mfma_f32_32x32x16_bf16 v[32:47], v[64:67], v[76:79], v[32:47]
	ds_read_b128 v[84:87], v105 offset:18432
	v_mfma_f32_32x32x16_bf16 v[16:31], v[68:71], v[72:75], v[16:31]
	ds_read_b128 v[88:91], v107 offset:16384
	v_mfma_f32_32x32x16_bf16 v[0:15], v[68:71], v[76:79], v[0:15]
	ds_read_b128 v[92:95], v107 offset:18432
	s_waitcnt vmcnt(8)
	s_waitcnt lgkmcnt(0)
	s_barrier
	ds_read_b128 v[64:67], v104 offset:32768
	ds_read_b128 v[68:71], v104 offset:34816
	ds_read_b128 v[72:75], v106 offset:32768
	ds_read_b128 v[76:79], v106 offset:34816
	s_add_u32 m0, s98, 0x4000
	v_mfma_f32_32x32x16_bf16 v[48:63], v[80:83], v[88:91], v[48:63]
	global_load_lds_dwordx4 v[96:97], off
	s_add_u32 m0, s98, 0x4400
	v_mfma_f32_32x32x16_bf16 v[32:47], v[80:83], v[92:95], v[32:47]
	global_load_lds_dwordx4 v[98:99], off
	s_add_u32 m0, s98, 0x6000
	v_mfma_f32_32x32x16_bf16 v[16:31], v[84:87], v[88:91], v[16:31]
	global_load_lds_dwordx4 v[100:101], off
	s_add_u32 m0, s98, 0x6400
	v_mfma_f32_32x32x16_bf16 v[0:15], v[84:87], v[92:95], v[0:15]
	global_load_lds_dwordx4 v[102:103], off
	v_lshl_add_u64 v[96:97], v[96:97], 0, 64
	v_lshl_add_u64 v[98:99], v[98:99], 0, 64
	v_lshl_add_u64 v[100:101], v[100:101], 0, 64
	v_lshl_add_u64 v[102:103], v[102:103], 0, 64
	s_waitcnt lgkmcnt(0)
	v_mfma_f32_32x32x16_bf16 v[48:63], v[64:67], v[72:75], v[48:63]
	ds_read_b128 v[80:83], v105 offset:32768
	v_mfma_f32_32x32x16_bf16 v[32:47], v[64:67], v[76:79], v[32:47]
	ds_read_b128 v[84:87], v105 offset:34816
	v_mfma_f32_32x32x16_bf16 v[16:31], v[68:71], v[72:75], v[16:31]
	ds_read_b128 v[88:91], v107 offset:32768
	v_mfma_f32_32x32x16_bf16 v[0:15], v[68:71], v[76:79], v[0:15]
	ds_read_b128 v[92:95], v107 offset:34816
	s_waitcnt vmcnt(8)
	s_waitcnt lgkmcnt(0)
	s_barrier
	ds_read_b128 v[64:67], v104 offset:49152
	ds_read_b128 v[68:71], v104 offset:51200
	ds_read_b128 v[72:75], v106 offset:49152
	ds_read_b128 v[76:79], v106 offset:51200
	s_add_u32 m0, s98, 0x8000
	v_mfma_f32_32x32x16_bf16 v[48:63], v[80:83], v[88:91], v[48:63]
	global_load_lds_dwordx4 v[96:97], off
	s_add_u32 m0, s98, 0x8400
	v_mfma_f32_32x32x16_bf16 v[32:47], v[80:83], v[92:95], v[32:47]
	global_load_lds_dwordx4 v[98:99], off
	s_add_u32 m0, s98, 0xa000
	v_mfma_f32_32x32x16_bf16 v[16:31], v[84:87], v[88:91], v[16:31]
	global_load_lds_dwordx4 v[100:101], off
	s_add_u32 m0, s98, 0xa400
	v_mfma_f32_32x32x16_bf16 v[0:15], v[84:87], v[92:95], v[0:15]
	global_load_lds_dwordx4 v[102:103], off
	v_lshl_add_u64 v[96:97], v[96:97], 0, 64
	v_lshl_add_u64 v[98:99], v[98:99], 0, 64
	v_lshl_add_u64 v[100:101], v[100:101], 0, 64
	v_lshl_add_u64 v[102:103], v[102:103], 0, 64
	s_waitcnt lgkmcnt(0)
	v_mfma_f32_32x32x16_bf16 v[48:63], v[64:67], v[72:75], v[48:63]
	ds_read_b128 v[80:83], v105 offset:49152
	v_mfma_f32_32x32x16_bf16 v[32:47], v[64:67], v[76:79], v[32:47]
	ds_read_b128 v[84:87], v105 offset:51200
	v_mfma_f32_32x32x16_bf16 v[16:31], v[68:71], v[72:75], v[16:31]
	ds_read_b128 v[88:91], v107 offset:49152
	v_mfma_f32_32x32x16_bf16 v[0:15], v[68:71], v[76:79], v[0:15]
	ds_read_b128 v[92:95], v107 offset:51200
	s_waitcnt vmcnt(8)
	s_waitcnt lgkmcnt(0)
	s_mov_b32 s99, 6
.Lmy_pre_p4_loop:
	s_barrier
	ds_read_b128 v[64:67], v104 offset:0
	ds_read_b128 v[68:71], v104 offset:2048
	ds_read_b128 v[72:75], v106 offset:0
	ds_read_b128 v[76:79], v106 offset:2048
	s_add_u32 m0, s98, 0xc000
	v_mfma_f32_32x32x16_bf16 v[48:63], v[80:83], v[88:91], v[48:63]
	global_load_lds_dwordx4 v[96:97], off
	s_add_u32 m0, s98, 0xc400
	v_mfma_f32_32x32x16_bf16 v[32:47], v[80:83], v[92:95], v[32:47]
	global_load_lds_dwordx4 v[98:99], off
	s_add_u32 m0, s98, 0xe000
	v_mfma_f32_32x32x16_bf16 v[16:31], v[84:87], v[88:91], v[16:31]
	global_load_lds_dwordx4 v[100:101], off
	s_add_u32 m0, s98, 0xe400
	v_mfma_f32_32x32x16_bf16 v[0:15], v[84:87], v[92:95], v[0:15]
	global_load_lds_dwordx4 v[102:103], off
	v_lshl_add_u64 v[96:97], v[96:97], 0, 64
	v_lshl_add_u64 v[98:99], v[98:99], 0, 64
	v_lshl_add_u64 v[100:101], v[100:101], 0, 64
	v_lshl_add_u64 v[102:103], v[102:103], 0, 64
	s_waitcnt lgkmcnt(0)
	v_mfma_f32_32x32x16_bf16 v[48:63], v[64:67], v[72:75], v[48:63]
	ds_read_b128 v[80:83], v105 offset:0
	v_mfma_f32_32x32x16_bf16 v[32:47], v[64:67], v[76:79], v[32:47]
	ds_read_b128 v[84:87], v105 offset:2048
	v_mfma_f32_32x32x16_bf16 v[16:31], v[68:71], v[72:75], v[16:31]
	ds_read_b128 v[88:91], v107 offset:0
	v_mfma_f32_32x32x16_bf16 v[0:15], v[68:71], v[76:79], v[0:15]
	ds_read_b128 v[92:95], v107 offset:2048
	s_waitcnt vmcnt(8)
	s_waitcnt lgkmcnt(0)
	s_barrier
; template <bool BNN, class AL, class BL>
; __device__ __forceinline__ void gemm_tile(const AL& al, const BL& bl, int K, u16* smem, f32x16 (&acc)[2][2]) {
;     ...
;   for (int kt = 0; kt < nkt; kt += 2) {
;     if (kt + 2 < nkt) G_LOAD(ra0, rb0, kt + 2)
;     G_COMPUTE(0)
;     if (kt + 1 < nkt) G_STORE(ra1, rb1, 1)
;     __syncthreads();
;     if (kt + 1 >= nkt) break;
;     if (kt + 3 < nkt) G_LOAD(ra1, rb1, kt + 3)
;     G_COMPUTE(1)
;     if (kt + 2 < nkt) G_STORE(ra0, rb0, 0)
;     __syncthreads();
;   }
	ds_read_b128 v[64:67], v104 offset:16384
	ds_read_b128 v[68:71], v104 offset:18432
	ds_read_b128 v[72:75], v106 offset:16384
	ds_read_b128 v[76:79], v106 offset:18432
	s_add_u32 m0, s98, 0x0
	v_mfma_f32_32x32x16_bf16 v[48:63], v[80:83], v[88:91], v[48:63]
	global_load_lds_dwordx4 v[96:97], off
	s_add_u32 m0, s98, 0x400
	v_mfma_f32_32x32x16_bf16 v[32:47], v[80:83], v[92:95], v[32:47]
	global_load_lds_dwordx4 v[98:99], off
	s_add_u32 m0, s98, 0x2000
	v_mfma_f32_32x32x16_bf16 v[16:31], v[84:87], v[88:91], v[16:31]
	global_load_lds_dwordx4 v[100:101], off
	s_add_u32 m0, s98, 0x2400
	v_mfma_f32_32x32x16_bf16 v[0:15], v[84:87], v[92:95], v[0:15]
	global_load_lds_dwordx4 v[102:103], off
	v_lshl_add_u64 v[96:97], v[96:97], 0, 64
	v_lshl_add_u64 v[98:99], v[98:99], 0, 64
	v_lshl_add_u64 v[100:101], v[100:101], 0, 64
	v_lshl_add_u64 v[102:103], v[102:103], 0, 64
	s_waitcnt lgkmcnt(0)
	v_mfma_f32_32x32x16_bf16 v[48:63], v[64:67], v[72:75], v[48:63]
	ds_read_b128 v[80:83], v105 offset:16384
	v_mfma_f32_32x32x16_bf16 v[32:47], v[64:67], v[76:79], v[32:47]
	ds_read_b128 v[84:87], v105 offset:18432
	v_mfma_f32_32x32x16_bf16 v[16:31], v[68:71], v[72:75], v[16:31]
	ds_read_b128 v[88:91], v107 offset:16384
	v_mfma_f32_32x32x16_bf16 v[0:15], v[68:71], v[76:79], v[0:15]
	ds_read_b128 v[92:95], v107 offset:18432
	s_waitcnt vmcnt(8)
	s_waitcnt lgkmcnt(0)
	s_barrier
	ds_read_b128 v[64:67], v104 offset:32768
	ds_read_b128 v[68:71], v104 offset:34816
	ds_read_b128 v[72:75], v106 offset:32768
	ds_read_b128 v[76:79], v106 offset:34816
	s_add_u32 m0, s98, 0x4000
	v_mfma_f32_32x32x16_bf16 v[48:63], v[80:83], v[88:91], v[48:63]
	global_load_lds_dwordx4 v[96:97], off
	s_add_u32 m0, s98, 0x4400
	v_mfma_f32_32x32x16_bf16 v[32:47], v[80:83], v[92:95], v[32:47]
	global_load_lds_dwordx4 v[98:99], off
	s_add_u32 m0, s98, 0x6000
	v_mfma_f32_32x32x16_bf16 v[16:31], v[84:87], v[88:91], v[16:31]
	global_load_lds_dwordx4 v[100:101], off
	s_add_u32 m0, s98, 0x6400
	v_mfma_f32_32x32x16_bf16 v[0:15], v[84:87], v[92:95], v[0:15]
	global_load_lds_dwordx4 v[102:103], off
	v_lshl_add_u64 v[96:97], v[96:97], 0, 64
	v_lshl_add_u64 v[98:99], v[98:99], 0, 64
	v_lshl_add_u64 v[100:101], v[100:101], 0, 64
	v_lshl_add_u64 v[102:103], v[102:103], 0, 64
	s_waitcnt lgkmcnt(0)
	v_mfma_f32_32x32x16_bf16 v[48:63], v[64:67], v[72:75], v[48:63]
	ds_read_b128 v[80:83], v105 offset:32768
	v_mfma_f32_32x32x16_bf16 v[32:47], v[64:67], v[76:79], v[32:47]
	ds_read_b128 v[84:87], v105 offset:34816
	v_mfma_f32_32x32x16_bf16 v[16:31], v[68:71], v[72:75], v[16:31]
	ds_read_b128 v[88:91], v107 offset:32768
	v_mfma_f32_32x32x16_bf16 v[0:15], v[68:71], v[76:79], v[0:15]
	ds_read_b128 v[92:95], v107 offset:34816
	s_waitcnt vmcnt(8)
	s_waitcnt lgkmcnt(0)
	s_barrier
	ds_read_b128 v[64:67], v104 offset:49152
	ds_read_b128 v[68:71], v104 offset:51200
	ds_read_b128 v[72:75], v106 offset:49152
	ds_read_b128 v[76:79], v106 offset:51200
	s_add_u32 m0, s98, 0x8000
	v_mfma_f32_32x32x16_bf16 v[48:63], v[80:83], v[88:91], v[48:63]
	global_load_lds_dwordx4 v[96:97], off
	s_add_u32 m0, s98, 0x8400
	v_mfma_f32_32x32x16_bf16 v[32:47], v[80:83], v[92:95], v[32:47]
	global_load_lds_dwordx4 v[98:99], off
	s_add_u32 m0, s98, 0xa000
	v_mfma_f32_32x32x16_bf16 v[16:31], v[84:87], v[88:91], v[16:31]
	global_load_lds_dwordx4 v[100:101], off
	s_add_u32 m0, s98, 0xa400
	v_mfma_f32_32x32x16_bf16 v[0:15], v[84:87], v[92:95], v[0:15]
	global_load_lds_dwordx4 v[102:103], off
	v_lshl_add_u64 v[96:97], v[96:97], 0, 64
	v_lshl_add_u64 v[98:99], v[98:99], 0, 64
	v_lshl_add_u64 v[100:101], v[100:101], 0, 64
	v_lshl_add_u64 v[102:103], v[102:103], 0, 64
	s_waitcnt lgkmcnt(0)
	v_mfma_f32_32x32x16_bf16 v[48:63], v[64:67], v[72:75], v[48:63]
	ds_read_b128 v[80:83], v105 offset:49152
	v_mfma_f32_32x32x16_bf16 v[32:47], v[64:67], v[76:79], v[32:47]
	ds_read_b128 v[84:87], v105 offset:51200
	v_mfma_f32_32x32x16_bf16 v[16:31], v[68:71], v[72:75], v[16:31]
	ds_read_b128 v[88:91], v107 offset:49152
	v_mfma_f32_32x32x16_bf16 v[0:15], v[68:71], v[76:79], v[0:15]
	ds_read_b128 v[92:95], v107 offset:51200
	s_waitcnt vmcnt(8)
	s_waitcnt lgkmcnt(0)
	s_sub_u32 s99, s99, 1
	s_cmp_lg_u32 s99, 0
	s_cbranch_scc1 .Lmy_pre_p4_loop
	s_barrier
	ds_read_b128 v[64:67], v104 offset:0
	ds_read_b128 v[68:71], v104 offset:2048
	ds_read_b128 v[72:75], v106 offset:0
	ds_read_b128 v[76:79], v106 offset:2048
	s_add_u32 m0, s98, 0xc000
	v_mfma_f32_32x32x16_bf16 v[48:63], v[80:83], v[88:91], v[48:63]
	global_load_lds_dwordx4 v[96:97], off
	s_add_u32 m0, s98, 0xc400
	v_mfma_f32_32x32x16_bf16 v[32:47], v[80:83], v[92:95], v[32:47]
	global_load_lds_dwordx4 v[98:99], off
	s_add_u32 m0, s98, 0xe000
	v_mfma_f32_32x32x16_bf16 v[16:31], v[84:87], v[88:91], v[16:31]
	global_load_lds_dwordx4 v[100:101], off
	s_add_u32 m0, s98, 0xe400
	v_mfma_f32_32x32x16_bf16 v[0:15], v[84:87], v[92:95], v[0:15]
	global_load_lds_dwordx4 v[102:103], off
	v_lshl_add_u64 v[96:97], v[96:97], 0, 64
	v_lshl_add_u64 v[98:99], v[98:99], 0, 64
	v_lshl_add_u64 v[100:101], v[100:101], 0, 64
	v_lshl_add_u64 v[102:103], v[102:103], 0, 64
	s_waitcnt lgkmcnt(0)
	v_mfma_f32_32x32x16_bf16 v[48:63], v[64:67], v[72:75], v[48:63]
	ds_read_b128 v[80:83], v105 offset:0
	v_mfma_f32_32x32x16_bf16 v[32:47], v[64:67], v[76:79], v[32:47]
	ds_read_b128 v[84:87], v105 offset:2048
	v_mfma_f32_32x32x16_bf16 v[16:31], v[68:71], v[72:75], v[16:31]
	ds_read_b128 v[88:91], v107 offset:0
	v_mfma_f32_32x32x16_bf16 v[0:15], v[68:71], v[76:79], v[0:15]
	ds_read_b128 v[92:95], v107 offset:2048
	s_waitcnt vmcnt(8)
	s_waitcnt lgkmcnt(0)
	s_barrier
; template <bool BNN, class AL, class BL>
; __device__ __forceinline__ void gemm_tile(const AL& al, const BL& bl, int K, u16* smem, f32x16 (&acc)[2][2]) {
;     ...
;   for (int kt = 0; kt < nkt; kt += 2) {
;     if (kt + 2 < nkt) G_LOAD(ra0, rb0, kt + 2)
;     G_COMPUTE(0)
;     if (kt + 1 < nkt) G_STORE(ra1, rb1, 1)
;     __syncthreads();
;     if (kt + 1 >= nkt) break;
;     if (kt + 3 < nkt) G_LOAD(ra1, rb1, kt + 3)
;     G_COMPUTE(1)
;     if (kt + 2 < nkt) G_STORE(ra0, rb0, 0)
;     __syncthreads();
;   }
; __device__ __forceinline__ void gemm_nt_phase(const u16* A, int lda, const u16* Bt, int ldb, u16* C, int ldc,
;                               int Mt, int Nt, int K, int qcols, float qscale, u16* smem,
;                               u16* vtx = nullptr, u16* vtc = nullptr, u16* smv = nullptr) {
;     ...
;       if (vtc != nullptr && ns >= 16) {
;         u16* Vb = vtc + (long)(ms >> 1) * 1024 * 256 + (long)(ns - 16) * 128 * 256 + (ms & 1) * 128;
;         ACC_FOREACH({ Vb[(unsigned)(col * 256 + row)] = f2bf(v); })
;       } else {
;         ACC_FOREACH({ Cb[(unsigned)(row * ldc + col)] = f2bf(v); })
	ds_read_b128 v[64:67], v104 offset:16384
	ds_read_b128 v[68:71], v104 offset:18432
	ds_read_b128 v[72:75], v106 offset:16384
	ds_read_b128 v[76:79], v106 offset:18432
	v_mfma_f32_32x32x16_bf16 v[48:63], v[80:83], v[88:91], v[48:63]
	v_mfma_f32_32x32x16_bf16 v[32:47], v[80:83], v[92:95], v[32:47]
	v_mfma_f32_32x32x16_bf16 v[16:31], v[84:87], v[88:91], v[16:31]
	v_mfma_f32_32x32x16_bf16 v[0:15], v[84:87], v[92:95], v[0:15]
	s_waitcnt lgkmcnt(0)
	v_mfma_f32_32x32x16_bf16 v[48:63], v[64:67], v[72:75], v[48:63]
	ds_read_b128 v[80:83], v105 offset:16384
	v_mfma_f32_32x32x16_bf16 v[32:47], v[64:67], v[76:79], v[32:47]
	ds_read_b128 v[84:87], v105 offset:18432
	v_mfma_f32_32x32x16_bf16 v[16:31], v[68:71], v[72:75], v[16:31]
	ds_read_b128 v[88:91], v107 offset:16384
	v_mfma_f32_32x32x16_bf16 v[0:15], v[68:71], v[76:79], v[0:15]
	ds_read_b128 v[92:95], v107 offset:18432
	s_waitcnt vmcnt(4)
	s_waitcnt lgkmcnt(0)
	s_barrier
	ds_read_b128 v[64:67], v104 offset:32768
	ds_read_b128 v[68:71], v104 offset:34816
	ds_read_b128 v[72:75], v106 offset:32768
	ds_read_b128 v[76:79], v106 offset:34816
	v_mfma_f32_32x32x16_bf16 v[48:63], v[80:83], v[88:91], v[48:63]
	v_mfma_f32_32x32x16_bf16 v[32:47], v[80:83], v[92:95], v[32:47]
	v_mfma_f32_32x32x16_bf16 v[16:31], v[84:87], v[88:91], v[16:31]
	v_mfma_f32_32x32x16_bf16 v[0:15], v[84:87], v[92:95], v[0:15]
	s_waitcnt lgkmcnt(0)
	v_mfma_f32_32x32x16_bf16 v[48:63], v[64:67], v[72:75], v[48:63]
	ds_read_b128 v[80:83], v105 offset:32768
	v_mfma_f32_32x32x16_bf16 v[32:47], v[64:67], v[76:79], v[32:47]
	ds_read_b128 v[84:87], v105 offset:34816
	v_mfma_f32_32x32x16_bf16 v[16:31], v[68:71], v[72:75], v[16:31]
	ds_read_b128 v[88:91], v107 offset:32768
	v_mfma_f32_32x32x16_bf16 v[0:15], v[68:71], v[76:79], v[0:15]
	ds_read_b128 v[92:95], v107 offset:34816
	s_waitcnt vmcnt(0)
	s_waitcnt lgkmcnt(0)
	s_barrier
	ds_read_b128 v[64:67], v104 offset:49152
	ds_read_b128 v[68:71], v104 offset:51200
	ds_read_b128 v[72:75], v106 offset:49152
	ds_read_b128 v[76:79], v106 offset:51200
	v_mfma_f32_32x32x16_bf16 v[48:63], v[80:83], v[88:91], v[48:63]
	v_mfma_f32_32x32x16_bf16 v[32:47], v[80:83], v[92:95], v[32:47]
	v_mfma_f32_32x32x16_bf16 v[16:31], v[84:87], v[88:91], v[16:31]
	v_mfma_f32_32x32x16_bf16 v[0:15], v[84:87], v[92:95], v[0:15]
	s_waitcnt lgkmcnt(0)
	v_mfma_f32_32x32x16_bf16 v[48:63], v[64:67], v[72:75], v[48:63]
	ds_read_b128 v[80:83], v105 offset:49152
	v_mfma_f32_32x32x16_bf16 v[32:47], v[64:67], v[76:79], v[32:47]
	ds_read_b128 v[84:87], v105 offset:51200
	v_mfma_f32_32x32x16_bf16 v[16:31], v[68:71], v[72:75], v[16:31]
	ds_read_b128 v[88:91], v107 offset:49152
	v_mfma_f32_32x32x16_bf16 v[0:15], v[68:71], v[76:79], v[0:15]
	ds_read_b128 v[92:95], v107 offset:51200
	s_waitcnt lgkmcnt(0)
	v_mfma_f32_32x32x16_bf16 v[48:63], v[80:83], v[88:91], v[48:63]
	v_mfma_f32_32x32x16_bf16 v[32:47], v[80:83], v[92:95], v[32:47]
	v_mfma_f32_32x32x16_bf16 v[16:31], v[84:87], v[88:91], v[16:31]
	v_mfma_f32_32x32x16_bf16 v[0:15], v[84:87], v[92:95], v[0:15]
	s_nop 15
	s_barrier
.LBB0_1370:
	v_cmp_gt_i32_e32 vcc, 16, v166
	s_or_b64 s[8:9], s[6:7], vcc
	s_and_saveexec_b64 s[10:11], s[8:9]
	s_xor_b64 s[8:9], exec, s[10:11]
	s_cbranch_execz .LBB0_1372
	v_mov_b64_e32 v[64:65], s[90:91]
	v_lshlrev_b32_e32 v66, 7, v166
	v_mad_i64_i32 v[64:65], s[10:11], v170, s17, v[64:65]
	v_ashrrev_i32_e32 v67, 31, v66
	v_lshl_add_u64 v[64:65], v[66:67], 1, v[64:65]
	v_mov_b32_e32 v66, v211
	v_cvt_pk_bf16_f32 v70, v49, s0
	v_lshrrev_b32_e32 v68, 3, v66
	v_lshrrev_b32_e32 v67, 1, v66
	v_and_b32_e32 v68, 4, v68
	s_waitcnt vmcnt(7)
	v_and_or_b32 v97, v67, s18, v68
	v_and_b32_e32 v96, 0x5f, v66
	v_mul_u32_u24_e32 v69, 0xc00, v97
	v_or_b32_e32 v130, v69, v96
	v_cvt_pk_bf16_f32 v68, v48, s0
	v_lshl_add_u64 v[66:67], v[130:131], 1, v[64:65]
	v_or_b32_e32 v98, 0xc00, v69
	global_store_short v[66:67], v68, off
	v_or_b32_e32 v68, v98, v96
	v_mov_b32_e32 v69, v131
	v_lshl_add_u64 v[68:69], v[68:69], 1, v[64:65]
	global_store_short v[68:69], v70, off
	v_add_u32_e32 v68, 0x1800, v130
	v_mov_b32_e32 v69, v131
	v_cvt_pk_bf16_f32 v70, v50, s0
	v_lshl_add_u64 v[68:69], v[68:69], 1, v[64:65]
	global_store_short v[68:69], v70, off
	v_add_u32_e32 v70, 0x2400, v130
	v_mov_b32_e32 v71, v131
	v_cvt_pk_bf16_f32 v72, v51, s0
	v_lshl_add_u64 v[70:71], v[70:71], 1, v[64:65]
	global_store_short v[70:71], v72, off
	v_add_u32_e32 v72, 0x6000, v130
	v_mov_b32_e32 v73, v131
	v_cvt_pk_bf16_f32 v74, v52, s0
	v_lshl_add_u64 v[72:73], v[72:73], 1, v[64:65]
	global_store_short v[72:73], v74, off
	v_add_u32_e32 v74, 0x6c00, v130
	v_mov_b32_e32 v75, v131
	v_cvt_pk_bf16_f32 v76, v53, s0
	v_lshl_add_u64 v[74:75], v[74:75], 1, v[64:65]
	global_store_short v[74:75], v76, off
	v_add_u32_e32 v76, 0x7800, v130
	v_mov_b32_e32 v77, v131
	v_cvt_pk_bf16_f32 v78, v54, s0
	v_lshl_add_u64 v[76:77], v[76:77], 1, v[64:65]
	global_store_short v[76:77], v78, off
	v_add_u32_e32 v78, 0x8400, v130
	v_mov_b32_e32 v79, v131
	v_cvt_pk_bf16_f32 v80, v55, s0
	v_lshl_add_u64 v[78:79], v[78:79], 1, v[64:65]
	global_store_short v[78:79], v80, off
	v_add_u32_e32 v80, 0xc000, v130
	v_mov_b32_e32 v81, v131
	v_cvt_pk_bf16_f32 v82, v56, s0
	v_lshl_add_u64 v[80:81], v[80:81], 1, v[64:65]
	global_store_short v[80:81], v82, off
	v_add_u32_e32 v82, 0xcc00, v130
	v_mov_b32_e32 v83, v131
	v_cvt_pk_bf16_f32 v84, v57, s0
	v_lshl_add_u64 v[82:83], v[82:83], 1, v[64:65]
	global_store_short v[82:83], v84, off
	v_add_u32_e32 v84, 0xd800, v130
	v_mov_b32_e32 v85, v131
	v_cvt_pk_bf16_f32 v86, v58, s0
	v_lshl_add_u64 v[84:85], v[84:85], 1, v[64:65]
	global_store_short v[84:85], v86, off
	v_add_u32_e32 v86, 0xe400, v130
	v_mov_b32_e32 v87, v131
	v_cvt_pk_bf16_f32 v88, v59, s0
	v_lshl_add_u64 v[86:87], v[86:87], 1, v[64:65]
	global_store_short v[86:87], v88, off
	v_add_u32_e32 v88, 0x12000, v130
	v_mov_b32_e32 v89, v131
	v_cvt_pk_bf16_f32 v90, v60, s0
	v_lshl_add_u64 v[88:89], v[88:89], 1, v[64:65]
	global_store_short v[88:89], v90, off
	v_add_u32_e32 v90, 0x12c00, v130
	v_mov_b32_e32 v91, v131
	v_cvt_pk_bf16_f32 v92, v61, s0
	v_lshl_add_u64 v[90:91], v[90:91], 1, v[64:65]
	global_store_short v[90:91], v92, off
	v_add_u32_e32 v92, 0x13800, v130
	v_mov_b32_e32 v93, v131
	v_cvt_pk_bf16_f32 v94, v62, s0
	v_lshl_add_u64 v[92:93], v[92:93], 1, v[64:65]
	global_store_short v[92:93], v94, off
	v_add_u32_e32 v94, 0x14400, v130
	v_mov_b32_e32 v95, v131
	v_cvt_pk_bf16_f32 v99, v63, s0
	v_lshl_add_u64 v[94:95], v[94:95], 1, v[64:65]
	global_store_short v[94:95], v99, off
	v_or_b32_e32 v99, 32, v96
	s_waitcnt vmcnt(22)
; __device__ __forceinline__ void gemm_nt_phase(const u16* A, int lda, const u16* Bt, int ldb, u16* C, int ldc,
;                               int Mt, int Nt, int K, int qcols, float qscale, u16* smem,
;                               u16* vtx = nullptr, u16* vtc = nullptr, u16* smv = nullptr) {
;     ...
;         ACC_FOREACH({ Cb[(unsigned)(row * ldc + col)] = f2bf(v); })
	v_cvt_pk_bf16_f32 v100, v32, s0
	global_store_short v[66:67], v100, off offset:64
	v_or_b32_e32 v66, v98, v99
	v_mov_b32_e32 v67, v131
	v_cvt_pk_bf16_f32 v100, v33, s0
	v_lshl_add_u64 v[66:67], v[66:67], 1, v[64:65]
	global_store_short v[66:67], v100, off
	v_cvt_pk_bf16_f32 v66, v34, s0
	global_store_short v[68:69], v66, off offset:64
	v_cvt_pk_bf16_f32 v66, v35, s0
	global_store_short v[70:71], v66, off offset:64
	v_cvt_pk_bf16_f32 v66, v36, s0
	global_store_short v[72:73], v66, off offset:64
	v_cvt_pk_bf16_f32 v66, v37, s0
	global_store_short v[74:75], v66, off offset:64
	v_cvt_pk_bf16_f32 v66, v38, s0
	global_store_short v[76:77], v66, off offset:64
	v_cvt_pk_bf16_f32 v66, v39, s0
	global_store_short v[78:79], v66, off offset:64
	v_cvt_pk_bf16_f32 v66, v40, s0
	global_store_short v[80:81], v66, off offset:64
	v_cvt_pk_bf16_f32 v66, v41, s0
	global_store_short v[82:83], v66, off offset:64
	v_cvt_pk_bf16_f32 v66, v42, s0
	global_store_short v[84:85], v66, off offset:64
	v_cvt_pk_bf16_f32 v66, v43, s0
	global_store_short v[86:87], v66, off offset:64
	v_cvt_pk_bf16_f32 v66, v44, s0
	global_store_short v[88:89], v66, off offset:64
	v_cvt_pk_bf16_f32 v66, v45, s0
	global_store_short v[90:91], v66, off offset:64
	v_cvt_pk_bf16_f32 v66, v46, s0
	global_store_short v[92:93], v66, off offset:64
	v_cvt_pk_bf16_f32 v66, v47, s0
	global_store_short v[94:95], v66, off offset:64
	v_add_u32_e32 v66, 0x18000, v130
	v_mov_b32_e32 v67, v131
	v_cvt_pk_bf16_f32 v68, v16, s0
	v_lshl_add_u64 v[66:67], v[66:67], 1, v[64:65]
	global_store_short v[66:67], v68, off
	v_add_u32_e32 v68, 0x18c00, v130
	v_mov_b32_e32 v69, v131
	v_cvt_pk_bf16_f32 v70, v17, s0
	v_lshl_add_u64 v[68:69], v[68:69], 1, v[64:65]
	global_store_short v[68:69], v70, off
	v_add_u32_e32 v70, 0x19800, v130
	v_mov_b32_e32 v71, v131
	v_cvt_pk_bf16_f32 v72, v18, s0
	v_lshl_add_u64 v[70:71], v[70:71], 1, v[64:65]
	global_store_short v[70:71], v72, off
	v_add_u32_e32 v72, 0x1a400, v130
	v_mov_b32_e32 v73, v131
	v_cvt_pk_bf16_f32 v74, v19, s0
	v_lshl_add_u64 v[72:73], v[72:73], 1, v[64:65]
	global_store_short v[72:73], v74, off
	v_add_u32_e32 v74, 0x1e000, v130
	v_mov_b32_e32 v75, v131
	v_cvt_pk_bf16_f32 v76, v20, s0
	v_lshl_add_u64 v[74:75], v[74:75], 1, v[64:65]
	global_store_short v[74:75], v76, off
	v_add_u32_e32 v76, 0x1ec00, v130
	v_mov_b32_e32 v77, v131
	v_cvt_pk_bf16_f32 v78, v21, s0
	v_lshl_add_u64 v[76:77], v[76:77], 1, v[64:65]
	global_store_short v[76:77], v78, off
	v_add_u32_e32 v78, 0x1f800, v130
	v_mov_b32_e32 v79, v131
	v_cvt_pk_bf16_f32 v80, v22, s0
	v_lshl_add_u64 v[78:79], v[78:79], 1, v[64:65]
	global_store_short v[78:79], v80, off
	v_add_u32_e32 v80, 0x20400, v130
	v_mov_b32_e32 v81, v131
	v_cvt_pk_bf16_f32 v82, v23, s0
	v_lshl_add_u64 v[80:81], v[80:81], 1, v[64:65]
	global_store_short v[80:81], v82, off
	v_add_u32_e32 v82, 0x24000, v130
	v_mov_b32_e32 v83, v131
	v_cvt_pk_bf16_f32 v84, v24, s0
	v_lshl_add_u64 v[82:83], v[82:83], 1, v[64:65]
	global_store_short v[82:83], v84, off
	v_add_u32_e32 v84, 0x24c00, v130
	v_mov_b32_e32 v85, v131
	v_cvt_pk_bf16_f32 v86, v25, s0
	v_lshl_add_u64 v[84:85], v[84:85], 1, v[64:65]
	global_store_short v[84:85], v86, off
	v_add_u32_e32 v86, 0x25800, v130
	v_mov_b32_e32 v87, v131
	v_cvt_pk_bf16_f32 v88, v26, s0
	v_lshl_add_u64 v[86:87], v[86:87], 1, v[64:65]
	global_store_short v[86:87], v88, off
	v_add_u32_e32 v88, 0x26400, v130
	v_mov_b32_e32 v89, v131
	v_cvt_pk_bf16_f32 v90, v27, s0
	v_lshl_add_u64 v[88:89], v[88:89], 1, v[64:65]
	global_store_short v[88:89], v90, off
	v_add_u32_e32 v90, 0x2a000, v130
	v_mov_b32_e32 v91, v131
	v_cvt_pk_bf16_f32 v92, v28, s0
	v_lshl_add_u64 v[90:91], v[90:91], 1, v[64:65]
	global_store_short v[90:91], v92, off
	v_add_u32_e32 v92, 0x2ac00, v130
	v_mov_b32_e32 v93, v131
	v_cvt_pk_bf16_f32 v94, v29, s0
	v_lshl_add_u64 v[92:93], v[92:93], 1, v[64:65]
	v_add_u32_e32 v130, 0x2b800, v130
	v_mad_u32_u24 v100, v97, s19, v212
	global_store_short v[92:93], v94, off
	v_cvt_pk_bf16_f32 v98, v30, s0
	v_lshl_add_u64 v[94:95], v[130:131], 1, v[64:65]
	v_or_b32_e32 v130, v100, v96
	global_store_short v[94:95], v98, off
	v_cvt_pk_bf16_f32 v98, v31, s0
	v_lshl_add_u64 v[96:97], v[130:131], 1, v[64:65]
	global_store_short v[96:97], v98, off
	v_cvt_pk_bf16_f32 v96, v0, s0
	global_store_short v[66:67], v96, off offset:64
	v_cvt_pk_bf16_f32 v66, v1, s0
	global_store_short v[68:69], v66, off offset:64
	v_cvt_pk_bf16_f32 v66, v2, s0
	global_store_short v[70:71], v66, off offset:64
	v_cvt_pk_bf16_f32 v66, v3, s0
	global_store_short v[72:73], v66, off offset:64
	v_cvt_pk_bf16_f32 v66, v4, s0
	global_store_short v[74:75], v66, off offset:64
	v_cvt_pk_bf16_f32 v66, v5, s0
	global_store_short v[76:77], v66, off offset:64
	v_cvt_pk_bf16_f32 v66, v6, s0
	global_store_short v[78:79], v66, off offset:64
	v_cvt_pk_bf16_f32 v66, v7, s0
	global_store_short v[80:81], v66, off offset:64
	v_cvt_pk_bf16_f32 v66, v8, s0
	global_store_short v[82:83], v66, off offset:64
	v_cvt_pk_bf16_f32 v66, v9, s0
	global_store_short v[84:85], v66, off offset:64
	v_cvt_pk_bf16_f32 v66, v10, s0
	global_store_short v[86:87], v66, off offset:64
	v_cvt_pk_bf16_f32 v66, v11, s0
	global_store_short v[88:89], v66, off offset:64
	v_cvt_pk_bf16_f32 v66, v12, s0
	global_store_short v[90:91], v66, off offset:64
	v_cvt_pk_bf16_f32 v66, v13, s0
	global_store_short v[92:93], v66, off offset:64
	v_cvt_pk_bf16_f32 v66, v14, s0
	global_store_short v[94:95], v66, off offset:64
	v_or_b32_e32 v130, v100, v99
